# mid-block s_setprio 0/1 pairs removed in the GEMM K-loops; forget_logits batching; x-loop counted wait
# speedup vs baseline: 1.0856x; 1.0856x over previous
; #define PG8_STAGE(bufoff, gbase, voff) do { _Pragma("unroll") for (int _i = 0; _i < 2; ++_i) \
;         __builtin_amdgcn_global_load_lds((const unsigned*)((const char*)(gbase) + (voff)[_i]), (PG8_LAS unsigned*)(lds + (bufoff) + ldsw + _i * 8192), 16, 0, 0); } while (0)
; #define PG8_LDA(dst, b, h) do { _Pragma("unroll") for (int m = 0; m < 4; ++m) _Pragma("unroll") for (int k = 0; k < 2; ++k) dst[m][k] = *(const PG8_LAS bf16x8*)(lds + PG8_SA(b, h) + aoff + m * 2048 + k * 1024); } while (0)
; #define PG8_LDB(dst, b, h) do { _Pragma("unroll") for (int n = 0; n < 2; ++n) _Pragma("unroll") for (int k = 0; k < 2; ++k) dst[n][k] = *(const PG8_LAS bf16x8*)(lds + PG8_SB(b, h) + boff + n * 2048 + k * 1024); } while (0)
; #define PG8_MMA(ai, bj, At, Bt) do { __builtin_amdgcn_s_setprio(1); _Pragma("unroll") for (int m = 0; m < 4; ++m) _Pragma("unroll") for (int n = 0; n < 2; ++n) _Pragma("unroll") for (int k = 0; k < 2; ++k) \
;         acc[ai][bj][m][n] = __builtin_amdgcn_mfma_f32_16x16x32_bf16(Bt[n][k], At[m][k], acc[ai][bj][m][n], 0, 0, 0); __builtin_amdgcn_s_setprio(0); } while (0)
; #define PG8_WAIT_V(n) asm volatile("s_waitcnt vmcnt(" #n ")" ::: "memory")
; #define PG8_WAIT_L(n) asm volatile("s_waitcnt lgkmcnt(" #n ")" ::: "memory")
; #define PG8_BAR __builtin_amdgcn_s_barrier()
; #define PG8_SCHED __builtin_amdgcn_sched_barrier(0)
; template <class Epi, class Sched, bool ALIGN_EPI = false, bool SP2 = false>
; __device__ __forceinline__ void gemm_phase(PG8_LAS unsigned char* lds, const Gemm g, const Sched& S, const Epi& E) {
;     ...
;         for (int t = 0; t < nt; t += 2) {
;             const bool last = (t == nt - 2);
;             const char* a1 = cA + (size_t)(t + 1) * kstep;
;             const char* a2 = last ? nA : cA + (size_t)(t + 2) * kstep; const char* b2 = last ? nB : cB + (size_t)(t + 2) * kstep;
;             const char* a3 = a2 + kstep; const char* b3 = b2 + kstep;
;             if (last && has_next) S.a_ready(nxt);
;             if constexpr (SP2) {
;             PG8_LDB(B0, 0, 0); PG8_LDB(B1, 0, 1); PG8_SCHED; PG8_LDA(At, 0, 0); PG8_STAGE(PG8_SA(1, 1), a1 + hstep, voffA);
;             PG8_WAIT_V(8); PG8_WAIT_L(0); PG8_BAR; PG8_MMA(0, 0, At, B0); PG8_MMA(0, 1, At, B1); PG8_BAR; PG8_SCHED;
;             PG8_LDA(At, 0, 1); PG8_STAGE(PG8_SB(0, 0), b2, voffB); PG8_STAGE(PG8_SB(0, 1), b2 + hstep, voffB); PG8_STAGE(PG8_SA(0, 0), a2, voffA);
.LBB0_132:
	s_add_u32 s18, s46, 0xfffc0080
	s_addc_u32 s38, s47, -1
	s_add_i32 s39, 0, 0x10000
	s_cmp_eq_u32 s85, 12
	s_cselect_b32 s81, s33, s38
	s_cselect_b32 s80, s73, s18
	v_add_u32_e32 v0, s39, v176
	s_cselect_b32 s45, s75, s84
	s_cselect_b32 s44, s82, s83
	s_add_i32 s18, 0, 0x14000
	ds_read_b128 v[144:147], v0
	ds_read_b128 v[148:151], v0 offset:1024
	ds_read_b128 v[152:155], v0 offset:2048
	ds_read_b128 v[156:159], v0 offset:3072
	v_add_u32_e32 v0, s18, v176
	ds_read_b128 v[160:163], v0
	ds_read_b128 v[164:167], v0 offset:1024
	ds_read_b128 v[168:171], v0 offset:2048
	ds_read_b128 v[172:175], v0 offset:3072
	v_lshl_add_u64 v[218:219], s[46:47], 0, v[140:141]
	s_add_i32 m0, s92, 0xc000
	ds_read_b128 v[180:183], v178
	ds_read_b128 v[184:187], v178 offset:1024
	ds_read_b128 v[188:191], v178 offset:2048
	ds_read_b128 v[192:195], v178 offset:3072
	ds_read_b128 v[202:205], v178 offset:4096
	ds_read_b128 v[206:209], v178 offset:5120
	ds_read_b128 v[210:213], v178 offset:6144
	ds_read_b128 v[214:217], v178 offset:7168
	global_load_lds_dwordx4 v[218:219], off
	v_lshl_add_u64 v[218:219], s[46:47], 0, v[142:143]
	s_add_i32 m0, s92, 0xe000
	s_nop 0
	global_load_lds_dwordx4 v[218:219], off
	s_waitcnt vmcnt(8)
	s_waitcnt lgkmcnt(0)
	s_barrier
	s_setprio 1
	s_waitcnt lgkmcnt(0)
	v_mfma_f32_16x16x32_bf16 v[118:121], v[144:147], v[180:183], v[118:121]
	v_mfma_f32_16x16x32_bf16 v[114:117], v[152:155], v[180:183], v[114:117]
	v_mfma_f32_16x16x32_bf16 v[102:105], v[144:147], v[188:191], v[102:105]
	v_mfma_f32_16x16x32_bf16 v[98:101], v[152:155], v[188:191], v[98:101]
	v_mfma_f32_16x16x32_bf16 v[86:89], v[144:147], v[202:205], v[86:89]
	v_mfma_f32_16x16x32_bf16 v[82:85], v[152:155], v[202:205], v[82:85]
	v_mfma_f32_16x16x32_bf16 v[70:73], v[144:147], v[210:213], v[70:73]
	v_mfma_f32_16x16x32_bf16 v[66:69], v[152:155], v[210:213], v[66:69]
	v_mfma_f32_16x16x32_bf16 v[118:121], v[148:151], v[184:187], v[118:121]
	v_mfma_f32_16x16x32_bf16 v[114:117], v[156:159], v[184:187], v[114:117]
	v_mfma_f32_16x16x32_bf16 v[102:105], v[148:151], v[192:195], v[102:105]
	v_mfma_f32_16x16x32_bf16 v[98:101], v[156:159], v[192:195], v[98:101]
	v_mfma_f32_16x16x32_bf16 v[86:89], v[148:151], v[206:209], v[86:89]
	v_mfma_f32_16x16x32_bf16 v[82:85], v[156:159], v[206:209], v[82:85]
	v_mfma_f32_16x16x32_bf16 v[70:73], v[148:151], v[214:217], v[70:73]
	v_mfma_f32_16x16x32_bf16 v[66:69], v[156:159], v[214:217], v[66:69]
	v_mfma_f32_16x16x32_bf16 v[126:129], v[160:163], v[180:183], v[126:129]
	v_mfma_f32_16x16x32_bf16 v[122:125], v[168:171], v[180:183], v[122:125]
	v_mfma_f32_16x16x32_bf16 v[110:113], v[160:163], v[188:191], v[110:113]
	v_mfma_f32_16x16x32_bf16 v[106:109], v[168:171], v[188:191], v[106:109]
	v_mfma_f32_16x16x32_bf16 v[94:97], v[160:163], v[202:205], v[94:97]
	v_mfma_f32_16x16x32_bf16 v[90:93], v[168:171], v[202:205], v[90:93]
	v_mfma_f32_16x16x32_bf16 v[78:81], v[160:163], v[210:213], v[78:81]
	v_mfma_f32_16x16x32_bf16 v[74:77], v[168:171], v[210:213], v[74:77]
	v_mfma_f32_16x16x32_bf16 v[126:129], v[164:167], v[184:187], v[126:129]
	v_mfma_f32_16x16x32_bf16 v[122:125], v[172:175], v[184:187], v[122:125]
	v_mfma_f32_16x16x32_bf16 v[110:113], v[164:167], v[192:195], v[110:113]
	v_mfma_f32_16x16x32_bf16 v[106:109], v[172:175], v[192:195], v[106:109]
	v_mfma_f32_16x16x32_bf16 v[94:97], v[164:167], v[206:209], v[94:97]
	v_mfma_f32_16x16x32_bf16 v[90:93], v[172:175], v[206:209], v[90:93]
	v_mfma_f32_16x16x32_bf16 v[78:81], v[164:167], v[214:217], v[78:81]
	v_mfma_f32_16x16x32_bf16 v[74:77], v[172:175], v[214:217], v[74:77]
	s_setprio 0
	s_barrier
	s_add_i32 s38, s39, s91
	v_lshl_add_u64 v[218:219], s[44:45], 0, v[134:135]
	s_mov_b32 m0, s38
	ds_read_b128 v[180:183], v178 offset:16384
	ds_read_b128 v[184:187], v178 offset:17408
	ds_read_b128 v[188:191], v178 offset:18432
	ds_read_b128 v[192:195], v178 offset:19456
	ds_read_b128 v[202:205], v178 offset:20480
	ds_read_b128 v[206:209], v178 offset:21504
	ds_read_b128 v[210:213], v178 offset:22528
	ds_read_b128 v[214:217], v178 offset:23552
	global_load_lds_dwordx4 v[218:219], off
	s_add_i32 m0, s38, 0x2000
	s_add_u32 s38, s44, 0x40000
	v_lshl_add_u64 v[220:221], s[44:45], 0, v[130:131]
	s_addc_u32 s39, s45, 0
	s_add_i32 s18, s18, s91
	global_load_lds_dwordx4 v[220:221], off
	v_lshl_add_u64 v[222:223], s[38:39], 0, v[134:135]
	s_mov_b32 m0, s18
	v_lshl_add_u64 v[224:225], s[80:81], 0, v[132:133]
	global_load_lds_dwordx4 v[222:223], off
	v_lshl_add_u64 v[222:223], s[38:39], 0, v[130:131]
	s_add_i32 m0, s18, 0x2000
	s_nop 0
	global_load_lds_dwordx4 v[222:223], off
	v_lshl_add_u64 v[222:223], s[80:81], 0, v[136:137]
	s_mov_b32 m0, s92
	s_nop 0
	global_load_lds_dwordx4 v[222:223], off
	s_mov_b32 m0, s93
	s_nop 0
	global_load_lds_dwordx4 v[224:225], off
	s_waitcnt vmcnt(8)
	s_waitcnt lgkmcnt(0)
	s_barrier
; #define PG8_STAGE(bufoff, gbase, voff) do { _Pragma("unroll") for (int _i = 0; _i < 2; ++_i) \
;         __builtin_amdgcn_global_load_lds((const unsigned*)((const char*)(gbase) + (voff)[_i]), (PG8_LAS unsigned*)(lds + (bufoff) + ldsw + _i * 8192), 16, 0, 0); } while (0)
; #define PG8_LDA(dst, b, h) do { _Pragma("unroll") for (int m = 0; m < 4; ++m) _Pragma("unroll") for (int k = 0; k < 2; ++k) dst[m][k] = *(const PG8_LAS bf16x8*)(lds + PG8_SA(b, h) + aoff + m * 2048 + k * 1024); } while (0)
; #define PG8_LDB(dst, b, h) do { _Pragma("unroll") for (int n = 0; n < 2; ++n) _Pragma("unroll") for (int k = 0; k < 2; ++k) dst[n][k] = *(const PG8_LAS bf16x8*)(lds + PG8_SB(b, h) + boff + n * 2048 + k * 1024); } while (0)
; #define PG8_MMA(ai, bj, At, Bt) do { __builtin_amdgcn_s_setprio(1); _Pragma("unroll") for (int m = 0; m < 4; ++m) _Pragma("unroll") for (int n = 0; n < 2; ++n) _Pragma("unroll") for (int k = 0; k < 2; ++k) \
;         acc[ai][bj][m][n] = __builtin_amdgcn_mfma_f32_16x16x32_bf16(Bt[n][k], At[m][k], acc[ai][bj][m][n], 0, 0, 0); __builtin_amdgcn_s_setprio(0); } while (0)
; #define PG8_WAIT_V(n) asm volatile("s_waitcnt vmcnt(" #n ")" ::: "memory")
; #define PG8_WAIT_L(n) asm volatile("s_waitcnt lgkmcnt(" #n ")" ::: "memory")
; #define PG8_BAR __builtin_amdgcn_s_barrier()
; #define PG8_SCHED __builtin_amdgcn_sched_barrier(0)
; template <class Epi, class Sched, bool ALIGN_EPI = false, bool SP2 = false>
; __device__ __forceinline__ void gemm_phase(PG8_LAS unsigned char* lds, const Gemm g, const Sched& S, const Epi& E) {
;     ...
;             PG8_WAIT_V(8); PG8_WAIT_L(0); PG8_BAR; PG8_MMA(1, 0, At, B0); PG8_MMA(1, 1, At, B1); PG8_BAR; PG8_SCHED;
;             PG8_LDB(B0, 1, 0); PG8_LDB(B1, 1, 1); PG8_SCHED; PG8_LDA(At, 1, 0); PG8_STAGE(PG8_SA(0, 1), a2 + hstep, voffA);
;             PG8_WAIT_V(8); PG8_WAIT_L(0); PG8_BAR; PG8_MMA(0, 0, At, B0); PG8_MMA(0, 1, At, B1); PG8_BAR; PG8_SCHED;
	s_setprio 1
	s_waitcnt lgkmcnt(0)
	v_mfma_f32_16x16x32_bf16 v[54:57], v[144:147], v[180:183], v[54:57]
	v_mfma_f32_16x16x32_bf16 v[50:53], v[152:155], v[180:183], v[50:53]
	v_mfma_f32_16x16x32_bf16 v[38:41], v[144:147], v[188:191], v[38:41]
	v_mfma_f32_16x16x32_bf16 v[34:37], v[152:155], v[188:191], v[34:37]
	v_mfma_f32_16x16x32_bf16 v[22:25], v[144:147], v[202:205], v[22:25]
	v_mfma_f32_16x16x32_bf16 v[18:21], v[152:155], v[202:205], v[18:21]
	v_mfma_f32_16x16x32_bf16 v[6:9], v[144:147], v[210:213], v[6:9]
	v_mfma_f32_16x16x32_bf16 v[2:5], v[152:155], v[210:213], v[2:5]
	v_mfma_f32_16x16x32_bf16 v[54:57], v[148:151], v[184:187], v[54:57]
	v_mfma_f32_16x16x32_bf16 v[50:53], v[156:159], v[184:187], v[50:53]
	v_mfma_f32_16x16x32_bf16 v[38:41], v[148:151], v[192:195], v[38:41]
	v_mfma_f32_16x16x32_bf16 v[34:37], v[156:159], v[192:195], v[34:37]
	v_mfma_f32_16x16x32_bf16 v[22:25], v[148:151], v[206:209], v[22:25]
	v_mfma_f32_16x16x32_bf16 v[18:21], v[156:159], v[206:209], v[18:21]
	v_mfma_f32_16x16x32_bf16 v[6:9], v[148:151], v[214:217], v[6:9]
	v_mfma_f32_16x16x32_bf16 v[2:5], v[156:159], v[214:217], v[2:5]
	v_mfma_f32_16x16x32_bf16 v[62:65], v[160:163], v[180:183], v[62:65]
	v_mfma_f32_16x16x32_bf16 v[58:61], v[168:171], v[180:183], v[58:61]
	v_mfma_f32_16x16x32_bf16 v[46:49], v[160:163], v[188:191], v[46:49]
	v_mfma_f32_16x16x32_bf16 v[42:45], v[168:171], v[188:191], v[42:45]
	v_mfma_f32_16x16x32_bf16 v[30:33], v[160:163], v[202:205], v[30:33]
	v_mfma_f32_16x16x32_bf16 v[26:29], v[168:171], v[202:205], v[26:29]
	v_mfma_f32_16x16x32_bf16 v[10:13], v[160:163], v[210:213], v[10:13]
	v_mfma_f32_16x16x32_bf16 v[14:17], v[168:171], v[210:213], v[14:17]
	v_mfma_f32_16x16x32_bf16 v[62:65], v[164:167], v[184:187], v[62:65]
	v_mfma_f32_16x16x32_bf16 v[58:61], v[172:175], v[184:187], v[58:61]
	v_mfma_f32_16x16x32_bf16 v[46:49], v[164:167], v[192:195], v[46:49]
	v_mfma_f32_16x16x32_bf16 v[42:45], v[172:175], v[192:195], v[42:45]
	v_mfma_f32_16x16x32_bf16 v[30:33], v[164:167], v[206:209], v[30:33]
	v_mfma_f32_16x16x32_bf16 v[26:29], v[172:175], v[206:209], v[26:29]
	v_mfma_f32_16x16x32_bf16 v[10:13], v[164:167], v[214:217], v[10:13]
	v_mfma_f32_16x16x32_bf16 v[14:17], v[172:175], v[214:217], v[14:17]
	s_setprio 0
	s_barrier
	s_add_i32 s18, 0, 0x18000
	v_add_u32_e32 v0, s18, v176
	s_add_i32 vcc_lo, 0, 0x1c000
	ds_read_b128 v[144:147], v0
	ds_read_b128 v[148:151], v0 offset:1024
	ds_read_b128 v[152:155], v0 offset:2048
	ds_read_b128 v[156:159], v0 offset:3072
	v_add_u32_e32 v0, vcc_lo, v176
	ds_read_b128 v[160:163], v0
	ds_read_b128 v[164:167], v0 offset:1024
	ds_read_b128 v[168:171], v0 offset:2048
	ds_read_b128 v[172:175], v0 offset:3072
	s_add_u32 s38, s80, 0x40000
	s_addc_u32 s39, s81, 0
	s_mov_b32 m0, s94
	v_lshl_add_u64 v[226:227], s[38:39], 0, v[136:137]
	ds_read_b128 v[180:183], v178 offset:32768
	ds_read_b128 v[184:187], v178 offset:33792
	ds_read_b128 v[188:191], v178 offset:34816
	ds_read_b128 v[192:195], v178 offset:35840
	ds_read_b128 v[202:205], v178 offset:36864
	ds_read_b128 v[206:209], v178 offset:37888
	ds_read_b128 v[210:213], v178 offset:38912
	ds_read_b128 v[214:217], v178 offset:39936
	global_load_lds_dwordx4 v[226:227], off
	v_lshl_add_u64 v[226:227], s[38:39], 0, v[132:133]
	s_mov_b32 m0, s95
	s_nop 0
	global_load_lds_dwordx4 v[226:227], off
	s_waitcnt vmcnt(8)
	s_waitcnt lgkmcnt(0)
	s_barrier
	s_setprio 1
	s_waitcnt lgkmcnt(0)
	v_mfma_f32_16x16x32_bf16 v[118:121], v[144:147], v[180:183], v[118:121]
	v_mfma_f32_16x16x32_bf16 v[114:117], v[152:155], v[180:183], v[114:117]
	v_mfma_f32_16x16x32_bf16 v[102:105], v[144:147], v[188:191], v[102:105]
	v_mfma_f32_16x16x32_bf16 v[98:101], v[152:155], v[188:191], v[98:101]
	v_mfma_f32_16x16x32_bf16 v[86:89], v[144:147], v[202:205], v[86:89]
	v_mfma_f32_16x16x32_bf16 v[82:85], v[152:155], v[202:205], v[82:85]
	v_mfma_f32_16x16x32_bf16 v[70:73], v[144:147], v[210:213], v[70:73]
	v_mfma_f32_16x16x32_bf16 v[66:69], v[152:155], v[210:213], v[66:69]
	v_mfma_f32_16x16x32_bf16 v[118:121], v[148:151], v[184:187], v[118:121]
	v_mfma_f32_16x16x32_bf16 v[114:117], v[156:159], v[184:187], v[114:117]
	v_mfma_f32_16x16x32_bf16 v[102:105], v[148:151], v[192:195], v[102:105]
	v_mfma_f32_16x16x32_bf16 v[98:101], v[156:159], v[192:195], v[98:101]
	v_mfma_f32_16x16x32_bf16 v[86:89], v[148:151], v[206:209], v[86:89]
	v_mfma_f32_16x16x32_bf16 v[82:85], v[156:159], v[206:209], v[82:85]
	v_mfma_f32_16x16x32_bf16 v[70:73], v[148:151], v[214:217], v[70:73]
	v_mfma_f32_16x16x32_bf16 v[66:69], v[156:159], v[214:217], v[66:69]
	v_mfma_f32_16x16x32_bf16 v[126:129], v[160:163], v[180:183], v[126:129]
	v_mfma_f32_16x16x32_bf16 v[122:125], v[168:171], v[180:183], v[122:125]
	v_mfma_f32_16x16x32_bf16 v[110:113], v[160:163], v[188:191], v[110:113]
	v_mfma_f32_16x16x32_bf16 v[106:109], v[168:171], v[188:191], v[106:109]
	v_mfma_f32_16x16x32_bf16 v[94:97], v[160:163], v[202:205], v[94:97]
	v_mfma_f32_16x16x32_bf16 v[90:93], v[168:171], v[202:205], v[90:93]
	v_mfma_f32_16x16x32_bf16 v[78:81], v[160:163], v[210:213], v[78:81]
	v_mfma_f32_16x16x32_bf16 v[74:77], v[168:171], v[210:213], v[74:77]
	v_mfma_f32_16x16x32_bf16 v[126:129], v[164:167], v[184:187], v[126:129]
	v_mfma_f32_16x16x32_bf16 v[122:125], v[172:175], v[184:187], v[122:125]
	v_mfma_f32_16x16x32_bf16 v[110:113], v[164:167], v[192:195], v[110:113]
	v_mfma_f32_16x16x32_bf16 v[106:109], v[172:175], v[192:195], v[106:109]
	v_mfma_f32_16x16x32_bf16 v[94:97], v[164:167], v[206:209], v[94:97]
	v_mfma_f32_16x16x32_bf16 v[90:93], v[172:175], v[206:209], v[90:93]
	v_mfma_f32_16x16x32_bf16 v[78:81], v[164:167], v[214:217], v[78:81]
	v_mfma_f32_16x16x32_bf16 v[74:77], v[172:175], v[214:217], v[74:77]
	s_setprio 0
	s_barrier
; #define PG8_STAGE(bufoff, gbase, voff) do { _Pragma("unroll") for (int _i = 0; _i < 2; ++_i) \
;         __builtin_amdgcn_global_load_lds((const unsigned*)((const char*)(gbase) + (voff)[_i]), (PG8_LAS unsigned*)(lds + (bufoff) + ldsw + _i * 8192), 16, 0, 0); } while (0)
; #define PG8_LDA(dst, b, h) do { _Pragma("unroll") for (int m = 0; m < 4; ++m) _Pragma("unroll") for (int k = 0; k < 2; ++k) dst[m][k] = *(const PG8_LAS bf16x8*)(lds + PG8_SA(b, h) + aoff + m * 2048 + k * 1024); } while (0)
; #define PG8_MMA(ai, bj, At, Bt) do { __builtin_amdgcn_s_setprio(1); _Pragma("unroll") for (int m = 0; m < 4; ++m) _Pragma("unroll") for (int n = 0; n < 2; ++n) _Pragma("unroll") for (int k = 0; k < 2; ++k) \
;         acc[ai][bj][m][n] = __builtin_amdgcn_mfma_f32_16x16x32_bf16(Bt[n][k], At[m][k], acc[ai][bj][m][n], 0, 0, 0); __builtin_amdgcn_s_setprio(0); } while (0)
; #define PG8_WAIT_V(n) asm volatile("s_waitcnt vmcnt(" #n ")" ::: "memory")
; #define PG8_WAIT_L(n) asm volatile("s_waitcnt lgkmcnt(" #n ")" ::: "memory")
; #define PG8_BAR __builtin_amdgcn_s_barrier()
; #define PG8_SCHED __builtin_amdgcn_sched_barrier(0)
; template <class Epi, class Sched, bool ALIGN_EPI = false, bool SP2 = false>
; __device__ __forceinline__ void gemm_phase(PG8_LAS unsigned char* lds, const Gemm g, const Sched& S, const Epi& E) {
;     ...
;         for (int t = 0; t < nt; t += 2) {
;     ...
;             PG8_LDA(At, 1, 1); PG8_STAGE(PG8_SB(1, 0), b3, voffB); PG8_STAGE(PG8_SB(1, 1), b3 + hstep, voffB); PG8_STAGE(PG8_SA(1, 0), a3, voffA);
;             PG8_WAIT_V(8); PG8_WAIT_L(0); PG8_BAR; PG8_MMA(1, 0, At, B0); PG8_MMA(1, 1, At, B1); PG8_BAR; PG8_SCHED;
	s_add_i32 s18, s18, s91
	v_lshl_add_u64 v[218:219], v[218:219], 0, s[30:31]
	s_mov_b32 m0, s18
	ds_read_b128 v[180:183], v178 offset:49152
	ds_read_b128 v[184:187], v178 offset:50176
	ds_read_b128 v[188:191], v178 offset:51200
	ds_read_b128 v[192:195], v178 offset:52224
	ds_read_b128 v[202:205], v178 offset:53248
	ds_read_b128 v[206:209], v178 offset:54272
	ds_read_b128 v[210:213], v178 offset:55296
	ds_read_b128 v[214:217], v178 offset:56320
	global_load_lds_dwordx4 v[218:219], off
	s_add_i32 m0, s18, 0x2000
	s_add_u32 s38, s44, 0x40080
	v_lshl_add_u64 v[218:219], v[220:221], 0, s[30:31]
	s_addc_u32 s39, s45, 0
	s_add_i32 s18, vcc_lo, s91
	global_load_lds_dwordx4 v[218:219], off
	v_lshl_add_u64 v[218:219], s[38:39], 0, v[134:135]
	s_mov_b32 m0, s18
	s_nop 0
	global_load_lds_dwordx4 v[218:219], off
	v_lshl_add_u64 v[218:219], s[38:39], 0, v[130:131]
	s_add_i32 m0, s18, 0x2000
	s_nop 0
	global_load_lds_dwordx4 v[218:219], off
	v_lshl_add_u64 v[218:219], v[222:223], 0, s[30:31]
	s_mov_b32 m0, s7
	s_nop 0
	global_load_lds_dwordx4 v[218:219], off
	v_lshl_add_u64 v[218:219], v[224:225], 0, s[30:31]
	s_mov_b32 m0, s96
	s_nop 0
	global_load_lds_dwordx4 v[218:219], off
	s_waitcnt vmcnt(8)
	s_waitcnt lgkmcnt(0)
	s_barrier
	s_setprio 1
	s_waitcnt lgkmcnt(0)
	v_mfma_f32_16x16x32_bf16 v[54:57], v[144:147], v[180:183], v[54:57]
	v_mfma_f32_16x16x32_bf16 v[50:53], v[152:155], v[180:183], v[50:53]
	v_mfma_f32_16x16x32_bf16 v[38:41], v[144:147], v[188:191], v[38:41]
	v_mfma_f32_16x16x32_bf16 v[34:37], v[152:155], v[188:191], v[34:37]
	v_mfma_f32_16x16x32_bf16 v[22:25], v[144:147], v[202:205], v[22:25]
	v_mfma_f32_16x16x32_bf16 v[18:21], v[152:155], v[202:205], v[18:21]
	v_mfma_f32_16x16x32_bf16 v[6:9], v[144:147], v[210:213], v[6:9]
	v_mfma_f32_16x16x32_bf16 v[2:5], v[152:155], v[210:213], v[2:5]
	v_mfma_f32_16x16x32_bf16 v[54:57], v[148:151], v[184:187], v[54:57]
	v_mfma_f32_16x16x32_bf16 v[50:53], v[156:159], v[184:187], v[50:53]
	v_mfma_f32_16x16x32_bf16 v[38:41], v[148:151], v[192:195], v[38:41]
	v_mfma_f32_16x16x32_bf16 v[34:37], v[156:159], v[192:195], v[34:37]
	v_mfma_f32_16x16x32_bf16 v[22:25], v[148:151], v[206:209], v[22:25]
	v_mfma_f32_16x16x32_bf16 v[18:21], v[156:159], v[206:209], v[18:21]
	v_mfma_f32_16x16x32_bf16 v[6:9], v[148:151], v[214:217], v[6:9]
	v_mfma_f32_16x16x32_bf16 v[2:5], v[156:159], v[214:217], v[2:5]
	v_mfma_f32_16x16x32_bf16 v[62:65], v[160:163], v[180:183], v[62:65]
	v_mfma_f32_16x16x32_bf16 v[58:61], v[168:171], v[180:183], v[58:61]
	v_mfma_f32_16x16x32_bf16 v[46:49], v[160:163], v[188:191], v[46:49]
	v_mfma_f32_16x16x32_bf16 v[42:45], v[168:171], v[188:191], v[42:45]
	v_mfma_f32_16x16x32_bf16 v[30:33], v[160:163], v[202:205], v[30:33]
	v_mfma_f32_16x16x32_bf16 v[26:29], v[168:171], v[202:205], v[26:29]
	v_mfma_f32_16x16x32_bf16 v[10:13], v[160:163], v[210:213], v[10:13]
	v_mfma_f32_16x16x32_bf16 v[14:17], v[168:171], v[210:213], v[14:17]
	v_mfma_f32_16x16x32_bf16 v[62:65], v[164:167], v[184:187], v[62:65]
	v_mfma_f32_16x16x32_bf16 v[58:61], v[172:175], v[184:187], v[58:61]
	v_mfma_f32_16x16x32_bf16 v[46:49], v[164:167], v[192:195], v[46:49]
	v_mfma_f32_16x16x32_bf16 v[42:45], v[172:175], v[192:195], v[42:45]
	v_mfma_f32_16x16x32_bf16 v[30:33], v[164:167], v[206:209], v[30:33]
	v_mfma_f32_16x16x32_bf16 v[26:29], v[172:175], v[206:209], v[26:29]
	v_mfma_f32_16x16x32_bf16 v[10:13], v[164:167], v[214:217], v[10:13]
	v_mfma_f32_16x16x32_bf16 v[14:17], v[172:175], v[214:217], v[14:17]
	s_setprio 0
	s_barrier
	s_add_i32 s85, s85, 2
	s_add_u32 s46, s46, 0x100
	s_addc_u32 s47, s47, 0
	s_add_u32 s83, s83, 0x100
	s_addc_u32 s84, s84, 0
	s_cmp_gt_u32 s85, 13
	s_cbranch_scc0 .LBB0_132
	s_and_b64 vcc, exec, s[10:11]
	s_cbranch_vccz .LBB0_135
	s_barrier

; #define PG8_STAGE(bufoff, gbase, voff) do { _Pragma("unroll") for (int _i = 0; _i < 2; ++_i) \
;         __builtin_amdgcn_global_load_lds((const unsigned*)((const char*)(gbase) + (voff)[_i]), (PG8_LAS unsigned*)(lds + (bufoff) + ldsw + _i * 8192), 16, 0, 0); } while (0)
; #define PG8_LDA(dst, b, h) do { _Pragma("unroll") for (int m = 0; m < 4; ++m) _Pragma("unroll") for (int k = 0; k < 2; ++k) dst[m][k] = *(const PG8_LAS bf16x8*)(lds + PG8_SA(b, h) + aoff + m * 2048 + k * 1024); } while (0)
; #define PG8_LDB(dst, b, h) do { _Pragma("unroll") for (int n = 0; n < 2; ++n) _Pragma("unroll") for (int k = 0; k < 2; ++k) dst[n][k] = *(const PG8_LAS bf16x8*)(lds + PG8_SB(b, h) + boff + n * 2048 + k * 1024); } while (0)
; #define PG8_MMA(ai, bj, At, Bt) do { __builtin_amdgcn_s_setprio(1); _Pragma("unroll") for (int m = 0; m < 4; ++m) _Pragma("unroll") for (int n = 0; n < 2; ++n) _Pragma("unroll") for (int k = 0; k < 2; ++k) \
;         acc[ai][bj][m][n] = __builtin_amdgcn_mfma_f32_16x16x32_bf16(Bt[n][k], At[m][k], acc[ai][bj][m][n], 0, 0, 0); __builtin_amdgcn_s_setprio(0); } while (0)
; #define PG8_WAIT_V(n) asm volatile("s_waitcnt vmcnt(" #n ")" ::: "memory")
; #define PG8_WAIT_L(n) asm volatile("s_waitcnt lgkmcnt(" #n ")" ::: "memory")
; #define PG8_BAR __builtin_amdgcn_s_barrier()
; #define PG8_SCHED __builtin_amdgcn_sched_barrier(0)
; template <class Epi, class Sched, bool ALIGN_EPI = false, bool SP2 = false>
; __device__ __forceinline__ void gemm_phase(PG8_LAS unsigned char* lds, const Gemm g, const Sched& S, const Epi& E) {
;     ...
;         for (int t = 0; t < nt; t += 2) {
;             const bool last = (t == nt - 2);
;             const char* a1 = cA + (size_t)(t + 1) * kstep;
;             const char* a2 = last ? nA : cA + (size_t)(t + 2) * kstep; const char* b2 = last ? nB : cB + (size_t)(t + 2) * kstep;
;             const char* a3 = a2 + kstep; const char* b3 = b2 + kstep;
;             if (last && has_next) S.a_ready(nxt);
;             if constexpr (SP2) {
;             PG8_LDB(B0, 0, 0); PG8_LDB(B1, 0, 1); PG8_SCHED; PG8_LDA(At, 0, 0); PG8_STAGE(PG8_SA(1, 1), a1 + hstep, voffA);
;             PG8_WAIT_V(8); PG8_WAIT_L(0); PG8_BAR; PG8_MMA(0, 0, At, B0); PG8_MMA(0, 1, At, B1); PG8_BAR; PG8_SCHED;
;             PG8_LDA(At, 0, 1); PG8_STAGE(PG8_SB(0, 0), b2, voffB); PG8_STAGE(PG8_SB(0, 1), b2 + hstep, voffB); PG8_STAGE(PG8_SA(0, 0), a2, voffA);
.LBB0_220:
	s_add_u32 s18, s60, 0xfffc0080
	s_addc_u32 s38, s61, -1
	s_add_i32 s39, 0, 0x10000
	s_cmp_eq_u32 s82, 12
	s_cselect_b32 s65, s47, s38
	s_cselect_b32 s64, s78, s18
	v_add_u32_e32 v145, s39, v141
	s_cselect_b32 s57, s49, s81
	s_cselect_b32 s56, s79, s80
	s_add_i32 s18, 0, 0x14000
	ds_read_b128 v[146:149], v145
	ds_read_b128 v[150:153], v145 offset:1024
	ds_read_b128 v[154:157], v145 offset:2048
	ds_read_b128 v[158:161], v145 offset:3072
	v_add_u32_e32 v145, s18, v141
	ds_read_b128 v[162:165], v145
	ds_read_b128 v[166:169], v145 offset:1024
	ds_read_b128 v[170:173], v145 offset:2048
	ds_read_b128 v[174:177], v145 offset:3072
	v_lshl_add_u64 v[194:195], s[60:61], 0, v[136:137]
	s_add_i32 m0, s29, 0xc000
	ds_read_b128 v[178:181], v144
	ds_read_b128 v[182:185], v144 offset:1024
	ds_read_b128 v[186:189], v144 offset:2048
	ds_read_b128 v[190:193], v144 offset:3072
	ds_read_b128 v[202:205], v144 offset:4096
	ds_read_b128 v[206:209], v144 offset:5120
	ds_read_b128 v[210:213], v144 offset:6144
	ds_read_b128 v[214:217], v144 offset:7168
	global_load_lds_dwordx4 v[194:195], off
	v_lshl_add_u64 v[194:195], s[60:61], 0, v[138:139]
	s_add_i32 m0, s29, 0xe000
	s_nop 0
	global_load_lds_dwordx4 v[194:195], off
	s_waitcnt vmcnt(8)
	s_waitcnt lgkmcnt(0)
	s_barrier
	s_setprio 1
	s_waitcnt lgkmcnt(0)
	v_mfma_f32_16x16x32_bf16 v[114:117], v[146:149], v[178:181], v[114:117]
	v_mfma_f32_16x16x32_bf16 v[118:121], v[154:157], v[178:181], v[118:121]
	v_mfma_f32_16x16x32_bf16 v[98:101], v[146:149], v[186:189], v[98:101]
	v_mfma_f32_16x16x32_bf16 v[102:105], v[154:157], v[186:189], v[102:105]
	v_mfma_f32_16x16x32_bf16 v[82:85], v[146:149], v[202:205], v[82:85]
	v_mfma_f32_16x16x32_bf16 v[86:89], v[154:157], v[202:205], v[86:89]
	v_mfma_f32_16x16x32_bf16 v[66:69], v[146:149], v[210:213], v[66:69]
	v_mfma_f32_16x16x32_bf16 v[70:73], v[154:157], v[210:213], v[70:73]
	v_mfma_f32_16x16x32_bf16 v[114:117], v[150:153], v[182:185], v[114:117]
	v_mfma_f32_16x16x32_bf16 v[118:121], v[158:161], v[182:185], v[118:121]
	v_mfma_f32_16x16x32_bf16 v[98:101], v[150:153], v[190:193], v[98:101]
	v_mfma_f32_16x16x32_bf16 v[102:105], v[158:161], v[190:193], v[102:105]
	v_mfma_f32_16x16x32_bf16 v[82:85], v[150:153], v[206:209], v[82:85]
	v_mfma_f32_16x16x32_bf16 v[86:89], v[158:161], v[206:209], v[86:89]
	v_mfma_f32_16x16x32_bf16 v[66:69], v[150:153], v[214:217], v[66:69]
	v_mfma_f32_16x16x32_bf16 v[70:73], v[158:161], v[214:217], v[70:73]
	v_mfma_f32_16x16x32_bf16 v[122:125], v[162:165], v[178:181], v[122:125]
	v_mfma_f32_16x16x32_bf16 v[126:129], v[170:173], v[178:181], v[126:129]
	v_mfma_f32_16x16x32_bf16 v[106:109], v[162:165], v[186:189], v[106:109]
	v_mfma_f32_16x16x32_bf16 v[110:113], v[170:173], v[186:189], v[110:113]
	v_mfma_f32_16x16x32_bf16 v[90:93], v[162:165], v[202:205], v[90:93]
	v_mfma_f32_16x16x32_bf16 v[94:97], v[170:173], v[202:205], v[94:97]
	v_mfma_f32_16x16x32_bf16 v[74:77], v[162:165], v[210:213], v[74:77]
	v_mfma_f32_16x16x32_bf16 v[78:81], v[170:173], v[210:213], v[78:81]
	v_mfma_f32_16x16x32_bf16 v[122:125], v[166:169], v[182:185], v[122:125]
	v_mfma_f32_16x16x32_bf16 v[126:129], v[174:177], v[182:185], v[126:129]
	v_mfma_f32_16x16x32_bf16 v[106:109], v[166:169], v[190:193], v[106:109]
	v_mfma_f32_16x16x32_bf16 v[110:113], v[174:177], v[190:193], v[110:113]
	v_mfma_f32_16x16x32_bf16 v[90:93], v[166:169], v[206:209], v[90:93]
	v_mfma_f32_16x16x32_bf16 v[94:97], v[174:177], v[206:209], v[94:97]
	v_mfma_f32_16x16x32_bf16 v[74:77], v[166:169], v[214:217], v[74:77]
	v_mfma_f32_16x16x32_bf16 v[78:81], v[174:177], v[214:217], v[78:81]
	s_setprio 0
	s_barrier
	s_add_i32 s38, s39, s27
	v_lshl_add_u64 v[194:195], s[56:57], 0, v[0:1]
	s_mov_b32 m0, s38
	ds_read_b128 v[178:181], v144 offset:16384
	ds_read_b128 v[182:185], v144 offset:17408
	ds_read_b128 v[186:189], v144 offset:18432
	ds_read_b128 v[190:193], v144 offset:19456
	ds_read_b128 v[202:205], v144 offset:20480
	ds_read_b128 v[206:209], v144 offset:21504
	ds_read_b128 v[210:213], v144 offset:22528
	ds_read_b128 v[214:217], v144 offset:23552
	global_load_lds_dwordx4 v[194:195], off
	s_add_i32 m0, s38, 0x2000
	s_add_u32 s38, s56, 0x40000
	v_lshl_add_u64 v[218:219], s[56:57], 0, v[130:131]
	s_addc_u32 s39, s57, 0
	s_add_i32 s18, s18, s27
	global_load_lds_dwordx4 v[218:219], off
	v_lshl_add_u64 v[220:221], s[38:39], 0, v[0:1]
	s_mov_b32 m0, s18
	v_lshl_add_u64 v[222:223], s[64:65], 0, v[132:133]
	global_load_lds_dwordx4 v[220:221], off
	v_lshl_add_u64 v[220:221], s[38:39], 0, v[130:131]
	s_add_i32 m0, s18, 0x2000
	s_nop 0
	global_load_lds_dwordx4 v[220:221], off
	v_lshl_add_u64 v[220:221], s[64:65], 0, v[134:135]
	s_mov_b32 m0, s29
	s_nop 0
	global_load_lds_dwordx4 v[220:221], off
	s_mov_b32 m0, s33
	s_nop 0
	global_load_lds_dwordx4 v[222:223], off
	s_waitcnt vmcnt(8)
	s_waitcnt lgkmcnt(0)
	s_barrier
; #define PG8_STAGE(bufoff, gbase, voff) do { _Pragma("unroll") for (int _i = 0; _i < 2; ++_i) \
;         __builtin_amdgcn_global_load_lds((const unsigned*)((const char*)(gbase) + (voff)[_i]), (PG8_LAS unsigned*)(lds + (bufoff) + ldsw + _i * 8192), 16, 0, 0); } while (0)
; #define PG8_LDA(dst, b, h) do { _Pragma("unroll") for (int m = 0; m < 4; ++m) _Pragma("unroll") for (int k = 0; k < 2; ++k) dst[m][k] = *(const PG8_LAS bf16x8*)(lds + PG8_SA(b, h) + aoff + m * 2048 + k * 1024); } while (0)
; #define PG8_LDB(dst, b, h) do { _Pragma("unroll") for (int n = 0; n < 2; ++n) _Pragma("unroll") for (int k = 0; k < 2; ++k) dst[n][k] = *(const PG8_LAS bf16x8*)(lds + PG8_SB(b, h) + boff + n * 2048 + k * 1024); } while (0)
; #define PG8_MMA(ai, bj, At, Bt) do { __builtin_amdgcn_s_setprio(1); _Pragma("unroll") for (int m = 0; m < 4; ++m) _Pragma("unroll") for (int n = 0; n < 2; ++n) _Pragma("unroll") for (int k = 0; k < 2; ++k) \
;         acc[ai][bj][m][n] = __builtin_amdgcn_mfma_f32_16x16x32_bf16(Bt[n][k], At[m][k], acc[ai][bj][m][n], 0, 0, 0); __builtin_amdgcn_s_setprio(0); } while (0)
; #define PG8_WAIT_V(n) asm volatile("s_waitcnt vmcnt(" #n ")" ::: "memory")
; #define PG8_WAIT_L(n) asm volatile("s_waitcnt lgkmcnt(" #n ")" ::: "memory")
; #define PG8_BAR __builtin_amdgcn_s_barrier()
; #define PG8_SCHED __builtin_amdgcn_sched_barrier(0)
; template <class Epi, class Sched, bool ALIGN_EPI = false, bool SP2 = false>
; __device__ __forceinline__ void gemm_phase(PG8_LAS unsigned char* lds, const Gemm g, const Sched& S, const Epi& E) {
;     ...
;             PG8_WAIT_V(8); PG8_WAIT_L(0); PG8_BAR; PG8_MMA(1, 0, At, B0); PG8_MMA(1, 1, At, B1); PG8_BAR; PG8_SCHED;
;             PG8_LDB(B0, 1, 0); PG8_LDB(B1, 1, 1); PG8_SCHED; PG8_LDA(At, 1, 0); PG8_STAGE(PG8_SA(0, 1), a2 + hstep, voffA);
;             PG8_WAIT_V(8); PG8_WAIT_L(0); PG8_BAR; PG8_MMA(0, 0, At, B0); PG8_MMA(0, 1, At, B1); PG8_BAR; PG8_SCHED;
	s_setprio 1
	s_waitcnt lgkmcnt(0)
	v_mfma_f32_16x16x32_bf16 v[50:53], v[146:149], v[178:181], v[50:53]
	v_mfma_f32_16x16x32_bf16 v[54:57], v[154:157], v[178:181], v[54:57]
	v_mfma_f32_16x16x32_bf16 v[34:37], v[146:149], v[186:189], v[34:37]
	v_mfma_f32_16x16x32_bf16 v[38:41], v[154:157], v[186:189], v[38:41]
	v_mfma_f32_16x16x32_bf16 v[18:21], v[146:149], v[202:205], v[18:21]
	v_mfma_f32_16x16x32_bf16 v[22:25], v[154:157], v[202:205], v[22:25]
	v_mfma_f32_16x16x32_bf16 v[2:5], v[146:149], v[210:213], v[2:5]
	v_mfma_f32_16x16x32_bf16 v[6:9], v[154:157], v[210:213], v[6:9]
	v_mfma_f32_16x16x32_bf16 v[50:53], v[150:153], v[182:185], v[50:53]
	v_mfma_f32_16x16x32_bf16 v[54:57], v[158:161], v[182:185], v[54:57]
	v_mfma_f32_16x16x32_bf16 v[34:37], v[150:153], v[190:193], v[34:37]
	v_mfma_f32_16x16x32_bf16 v[38:41], v[158:161], v[190:193], v[38:41]
	v_mfma_f32_16x16x32_bf16 v[18:21], v[150:153], v[206:209], v[18:21]
	v_mfma_f32_16x16x32_bf16 v[22:25], v[158:161], v[206:209], v[22:25]
	v_mfma_f32_16x16x32_bf16 v[2:5], v[150:153], v[214:217], v[2:5]
	v_mfma_f32_16x16x32_bf16 v[6:9], v[158:161], v[214:217], v[6:9]
	v_mfma_f32_16x16x32_bf16 v[58:61], v[162:165], v[178:181], v[58:61]
	v_mfma_f32_16x16x32_bf16 v[62:65], v[170:173], v[178:181], v[62:65]
	v_mfma_f32_16x16x32_bf16 v[42:45], v[162:165], v[186:189], v[42:45]
	v_mfma_f32_16x16x32_bf16 v[46:49], v[170:173], v[186:189], v[46:49]
	v_mfma_f32_16x16x32_bf16 v[26:29], v[162:165], v[202:205], v[26:29]
	v_mfma_f32_16x16x32_bf16 v[30:33], v[170:173], v[202:205], v[30:33]
	v_mfma_f32_16x16x32_bf16 v[10:13], v[162:165], v[210:213], v[10:13]
	v_mfma_f32_16x16x32_bf16 v[14:17], v[170:173], v[210:213], v[14:17]
	v_mfma_f32_16x16x32_bf16 v[58:61], v[166:169], v[182:185], v[58:61]
	v_mfma_f32_16x16x32_bf16 v[62:65], v[174:177], v[182:185], v[62:65]
	v_mfma_f32_16x16x32_bf16 v[42:45], v[166:169], v[190:193], v[42:45]
	v_mfma_f32_16x16x32_bf16 v[46:49], v[174:177], v[190:193], v[46:49]
	v_mfma_f32_16x16x32_bf16 v[26:29], v[166:169], v[206:209], v[26:29]
	v_mfma_f32_16x16x32_bf16 v[30:33], v[174:177], v[206:209], v[30:33]
	v_mfma_f32_16x16x32_bf16 v[10:13], v[166:169], v[214:217], v[10:13]
	v_mfma_f32_16x16x32_bf16 v[14:17], v[174:177], v[214:217], v[14:17]
	s_setprio 0
	s_barrier
	s_add_i32 s18, 0, 0x18000
	v_add_u32_e32 v145, s18, v141
	s_add_i32 s83, 0, 0x1c000
	ds_read_b128 v[146:149], v145
	ds_read_b128 v[150:153], v145 offset:1024
	ds_read_b128 v[154:157], v145 offset:2048
	ds_read_b128 v[158:161], v145 offset:3072
	v_add_u32_e32 v145, s83, v141
	ds_read_b128 v[162:165], v145
	ds_read_b128 v[166:169], v145 offset:1024
	ds_read_b128 v[170:173], v145 offset:2048
	ds_read_b128 v[174:177], v145 offset:3072
	s_add_u32 s38, s64, 0x40000
	s_addc_u32 s39, s65, 0
	s_mov_b32 m0, s58
	v_lshl_add_u64 v[224:225], s[38:39], 0, v[134:135]
	ds_read_b128 v[178:181], v144 offset:32768
	ds_read_b128 v[182:185], v144 offset:33792
	ds_read_b128 v[186:189], v144 offset:34816
	ds_read_b128 v[190:193], v144 offset:35840
	ds_read_b128 v[202:205], v144 offset:36864
	ds_read_b128 v[206:209], v144 offset:37888
	ds_read_b128 v[210:213], v144 offset:38912
	ds_read_b128 v[214:217], v144 offset:39936
	global_load_lds_dwordx4 v[224:225], off
	v_lshl_add_u64 v[224:225], s[38:39], 0, v[132:133]
	s_mov_b32 m0, s69
	s_nop 0
	global_load_lds_dwordx4 v[224:225], off
	s_waitcnt vmcnt(8)
	s_waitcnt lgkmcnt(0)
	s_barrier
	s_setprio 1
	s_waitcnt lgkmcnt(0)
	v_mfma_f32_16x16x32_bf16 v[114:117], v[146:149], v[178:181], v[114:117]
	v_mfma_f32_16x16x32_bf16 v[118:121], v[154:157], v[178:181], v[118:121]
	v_mfma_f32_16x16x32_bf16 v[98:101], v[146:149], v[186:189], v[98:101]
	v_mfma_f32_16x16x32_bf16 v[102:105], v[154:157], v[186:189], v[102:105]
	v_mfma_f32_16x16x32_bf16 v[82:85], v[146:149], v[202:205], v[82:85]
	v_mfma_f32_16x16x32_bf16 v[86:89], v[154:157], v[202:205], v[86:89]
	v_mfma_f32_16x16x32_bf16 v[66:69], v[146:149], v[210:213], v[66:69]
	v_mfma_f32_16x16x32_bf16 v[70:73], v[154:157], v[210:213], v[70:73]
	v_mfma_f32_16x16x32_bf16 v[114:117], v[150:153], v[182:185], v[114:117]
	v_mfma_f32_16x16x32_bf16 v[118:121], v[158:161], v[182:185], v[118:121]
	v_mfma_f32_16x16x32_bf16 v[98:101], v[150:153], v[190:193], v[98:101]
	v_mfma_f32_16x16x32_bf16 v[102:105], v[158:161], v[190:193], v[102:105]
	v_mfma_f32_16x16x32_bf16 v[82:85], v[150:153], v[206:209], v[82:85]
	v_mfma_f32_16x16x32_bf16 v[86:89], v[158:161], v[206:209], v[86:89]
	v_mfma_f32_16x16x32_bf16 v[66:69], v[150:153], v[214:217], v[66:69]
	v_mfma_f32_16x16x32_bf16 v[70:73], v[158:161], v[214:217], v[70:73]
	v_mfma_f32_16x16x32_bf16 v[122:125], v[162:165], v[178:181], v[122:125]
	v_mfma_f32_16x16x32_bf16 v[126:129], v[170:173], v[178:181], v[126:129]
	v_mfma_f32_16x16x32_bf16 v[106:109], v[162:165], v[186:189], v[106:109]
	v_mfma_f32_16x16x32_bf16 v[110:113], v[170:173], v[186:189], v[110:113]
	v_mfma_f32_16x16x32_bf16 v[90:93], v[162:165], v[202:205], v[90:93]
	v_mfma_f32_16x16x32_bf16 v[94:97], v[170:173], v[202:205], v[94:97]
	v_mfma_f32_16x16x32_bf16 v[74:77], v[162:165], v[210:213], v[74:77]
	v_mfma_f32_16x16x32_bf16 v[78:81], v[170:173], v[210:213], v[78:81]
	v_mfma_f32_16x16x32_bf16 v[122:125], v[166:169], v[182:185], v[122:125]
	v_mfma_f32_16x16x32_bf16 v[126:129], v[174:177], v[182:185], v[126:129]
	v_mfma_f32_16x16x32_bf16 v[106:109], v[166:169], v[190:193], v[106:109]
	v_mfma_f32_16x16x32_bf16 v[110:113], v[174:177], v[190:193], v[110:113]
	v_mfma_f32_16x16x32_bf16 v[90:93], v[166:169], v[206:209], v[90:93]
	v_mfma_f32_16x16x32_bf16 v[94:97], v[174:177], v[206:209], v[94:97]
	v_mfma_f32_16x16x32_bf16 v[74:77], v[166:169], v[214:217], v[74:77]
	v_mfma_f32_16x16x32_bf16 v[78:81], v[174:177], v[214:217], v[78:81]
	s_setprio 0
	s_barrier
; #define PG8_STAGE(bufoff, gbase, voff) do { _Pragma("unroll") for (int _i = 0; _i < 2; ++_i) \
;         __builtin_amdgcn_global_load_lds((const unsigned*)((const char*)(gbase) + (voff)[_i]), (PG8_LAS unsigned*)(lds + (bufoff) + ldsw + _i * 8192), 16, 0, 0); } while (0)
; #define PG8_LDA(dst, b, h) do { _Pragma("unroll") for (int m = 0; m < 4; ++m) _Pragma("unroll") for (int k = 0; k < 2; ++k) dst[m][k] = *(const PG8_LAS bf16x8*)(lds + PG8_SA(b, h) + aoff + m * 2048 + k * 1024); } while (0)
; #define PG8_MMA(ai, bj, At, Bt) do { __builtin_amdgcn_s_setprio(1); _Pragma("unroll") for (int m = 0; m < 4; ++m) _Pragma("unroll") for (int n = 0; n < 2; ++n) _Pragma("unroll") for (int k = 0; k < 2; ++k) \
;         acc[ai][bj][m][n] = __builtin_amdgcn_mfma_f32_16x16x32_bf16(Bt[n][k], At[m][k], acc[ai][bj][m][n], 0, 0, 0); __builtin_amdgcn_s_setprio(0); } while (0)
; #define PG8_WAIT_V(n) asm volatile("s_waitcnt vmcnt(" #n ")" ::: "memory")
; #define PG8_WAIT_L(n) asm volatile("s_waitcnt lgkmcnt(" #n ")" ::: "memory")
; #define PG8_BAR __builtin_amdgcn_s_barrier()
; #define PG8_SCHED __builtin_amdgcn_sched_barrier(0)
; template <class Epi, class Sched, bool ALIGN_EPI = false, bool SP2 = false>
; __device__ __forceinline__ void gemm_phase(PG8_LAS unsigned char* lds, const Gemm g, const Sched& S, const Epi& E) {
;     ...
;         for (int t = 0; t < nt; t += 2) {
;     ...
;             PG8_LDA(At, 1, 1); PG8_STAGE(PG8_SB(1, 0), b3, voffB); PG8_STAGE(PG8_SB(1, 1), b3 + hstep, voffB); PG8_STAGE(PG8_SA(1, 0), a3, voffA);
;             PG8_WAIT_V(8); PG8_WAIT_L(0); PG8_BAR; PG8_MMA(1, 0, At, B0); PG8_MMA(1, 1, At, B1); PG8_BAR; PG8_SCHED;
	s_add_i32 s18, s18, s27
	v_lshl_add_u64 v[194:195], v[194:195], 0, s[30:31]
	s_mov_b32 m0, s18
	ds_read_b128 v[178:181], v144 offset:49152
	ds_read_b128 v[182:185], v144 offset:50176
	ds_read_b128 v[186:189], v144 offset:51200
	ds_read_b128 v[190:193], v144 offset:52224
	ds_read_b128 v[202:205], v144 offset:53248
	ds_read_b128 v[206:209], v144 offset:54272
	ds_read_b128 v[210:213], v144 offset:55296
	ds_read_b128 v[214:217], v144 offset:56320
	global_load_lds_dwordx4 v[194:195], off
	s_add_i32 m0, s18, 0x2000
	s_add_u32 s38, s56, 0x40080
	v_lshl_add_u64 v[194:195], v[218:219], 0, s[30:31]
	s_addc_u32 s39, s57, 0
	s_add_i32 s18, s83, s27
	global_load_lds_dwordx4 v[194:195], off
	v_lshl_add_u64 v[194:195], s[38:39], 0, v[0:1]
	s_mov_b32 m0, s18
	s_nop 0
	global_load_lds_dwordx4 v[194:195], off
	v_lshl_add_u64 v[194:195], s[38:39], 0, v[130:131]
	s_add_i32 m0, s18, 0x2000
	s_nop 0
	global_load_lds_dwordx4 v[194:195], off
	v_lshl_add_u64 v[194:195], v[220:221], 0, s[30:31]
	s_mov_b32 m0, s71
	s_nop 0
	global_load_lds_dwordx4 v[194:195], off
	v_lshl_add_u64 v[194:195], v[222:223], 0, s[30:31]
	s_mov_b32 m0, s72
	s_nop 0
	global_load_lds_dwordx4 v[194:195], off
	s_waitcnt vmcnt(8)
	s_waitcnt lgkmcnt(0)
	s_barrier
	s_setprio 1
	s_waitcnt lgkmcnt(0)
	v_mfma_f32_16x16x32_bf16 v[50:53], v[146:149], v[178:181], v[50:53]
	v_mfma_f32_16x16x32_bf16 v[54:57], v[154:157], v[178:181], v[54:57]
	v_mfma_f32_16x16x32_bf16 v[34:37], v[146:149], v[186:189], v[34:37]
	v_mfma_f32_16x16x32_bf16 v[38:41], v[154:157], v[186:189], v[38:41]
	v_mfma_f32_16x16x32_bf16 v[18:21], v[146:149], v[202:205], v[18:21]
	v_mfma_f32_16x16x32_bf16 v[22:25], v[154:157], v[202:205], v[22:25]
	v_mfma_f32_16x16x32_bf16 v[2:5], v[146:149], v[210:213], v[2:5]
	v_mfma_f32_16x16x32_bf16 v[6:9], v[154:157], v[210:213], v[6:9]
	v_mfma_f32_16x16x32_bf16 v[50:53], v[150:153], v[182:185], v[50:53]
	v_mfma_f32_16x16x32_bf16 v[54:57], v[158:161], v[182:185], v[54:57]
	v_mfma_f32_16x16x32_bf16 v[34:37], v[150:153], v[190:193], v[34:37]
	v_mfma_f32_16x16x32_bf16 v[38:41], v[158:161], v[190:193], v[38:41]
	v_mfma_f32_16x16x32_bf16 v[18:21], v[150:153], v[206:209], v[18:21]
	v_mfma_f32_16x16x32_bf16 v[22:25], v[158:161], v[206:209], v[22:25]
	v_mfma_f32_16x16x32_bf16 v[2:5], v[150:153], v[214:217], v[2:5]
	v_mfma_f32_16x16x32_bf16 v[6:9], v[158:161], v[214:217], v[6:9]
	v_mfma_f32_16x16x32_bf16 v[58:61], v[162:165], v[178:181], v[58:61]
	v_mfma_f32_16x16x32_bf16 v[62:65], v[170:173], v[178:181], v[62:65]
	v_mfma_f32_16x16x32_bf16 v[42:45], v[162:165], v[186:189], v[42:45]
	v_mfma_f32_16x16x32_bf16 v[46:49], v[170:173], v[186:189], v[46:49]
	v_mfma_f32_16x16x32_bf16 v[26:29], v[162:165], v[202:205], v[26:29]
	v_mfma_f32_16x16x32_bf16 v[30:33], v[170:173], v[202:205], v[30:33]
	v_mfma_f32_16x16x32_bf16 v[10:13], v[162:165], v[210:213], v[10:13]
	v_mfma_f32_16x16x32_bf16 v[14:17], v[170:173], v[210:213], v[14:17]
	v_mfma_f32_16x16x32_bf16 v[58:61], v[166:169], v[182:185], v[58:61]
	v_mfma_f32_16x16x32_bf16 v[62:65], v[174:177], v[182:185], v[62:65]
	v_mfma_f32_16x16x32_bf16 v[42:45], v[166:169], v[190:193], v[42:45]
	v_mfma_f32_16x16x32_bf16 v[46:49], v[174:177], v[190:193], v[46:49]
	v_mfma_f32_16x16x32_bf16 v[26:29], v[166:169], v[206:209], v[26:29]
	v_mfma_f32_16x16x32_bf16 v[30:33], v[174:177], v[206:209], v[30:33]
	v_mfma_f32_16x16x32_bf16 v[10:13], v[166:169], v[214:217], v[10:13]
	v_mfma_f32_16x16x32_bf16 v[14:17], v[174:177], v[214:217], v[14:17]
	s_setprio 0
	s_barrier
	s_add_i32 s82, s82, 2
	s_add_u32 s60, s60, 0x100
	s_addc_u32 s61, s61, 0
	s_add_u32 s80, s80, 0x100
	s_addc_u32 s81, s81, 0
	s_cmp_gt_u32 s82, 13
	s_cbranch_scc0 .LBB0_220
	s_and_b64 vcc, exec, s[44:45]
	s_cbranch_vccz .LBB0_223
	s_barrier

; #define PG8_STAGE(bufoff, gbase, voff) do { _Pragma("unroll") for (int _i = 0; _i < 2; ++_i) \
;         __builtin_amdgcn_global_load_lds((const unsigned*)((const char*)(gbase) + (voff)[_i]), (PG8_LAS unsigned*)(lds + (bufoff) + ldsw + _i * 8192), 16, 0, 0); } while (0)
; #define PG8_LDA(dst, b, h) do { _Pragma("unroll") for (int m = 0; m < 4; ++m) _Pragma("unroll") for (int k = 0; k < 2; ++k) dst[m][k] = *(const PG8_LAS bf16x8*)(lds + PG8_SA(b, h) + aoff + m * 2048 + k * 1024); } while (0)
; #define PG8_LDB(dst, b, h) do { _Pragma("unroll") for (int n = 0; n < 2; ++n) _Pragma("unroll") for (int k = 0; k < 2; ++k) dst[n][k] = *(const PG8_LAS bf16x8*)(lds + PG8_SB(b, h) + boff + n * 2048 + k * 1024); } while (0)
; #define PG8_MMA(ai, bj, At, Bt) do { __builtin_amdgcn_s_setprio(1); _Pragma("unroll") for (int m = 0; m < 4; ++m) _Pragma("unroll") for (int n = 0; n < 2; ++n) _Pragma("unroll") for (int k = 0; k < 2; ++k) \
;         acc[ai][bj][m][n] = __builtin_amdgcn_mfma_f32_16x16x32_bf16(Bt[n][k], At[m][k], acc[ai][bj][m][n], 0, 0, 0); __builtin_amdgcn_s_setprio(0); } while (0)
; #define PG8_WAIT_V(n) asm volatile("s_waitcnt vmcnt(" #n ")" ::: "memory")
; #define PG8_WAIT_L(n) asm volatile("s_waitcnt lgkmcnt(" #n ")" ::: "memory")
; #define PG8_BAR __builtin_amdgcn_s_barrier()
; #define PG8_SCHED __builtin_amdgcn_sched_barrier(0)
; template <class Epi, class Sched, bool ALIGN_EPI = false, bool SP2 = false>
; __device__ __forceinline__ void gemm_phase(PG8_LAS unsigned char* lds, const Gemm g, const Sched& S, const Epi& E) {
;     ...
;         for (int t = 0; t < nt; t += 2) {
;             const bool last = (t == nt - 2);
;             const char* a1 = cA + (size_t)(t + 1) * kstep;
;             const char* a2 = last ? nA : cA + (size_t)(t + 2) * kstep; const char* b2 = last ? nB : cB + (size_t)(t + 2) * kstep;
;             const char* a3 = a2 + kstep; const char* b3 = b2 + kstep;
;             if (last && has_next) S.a_ready(nxt);
;             if constexpr (SP2) {
;             PG8_LDB(B0, 0, 0); PG8_LDB(B1, 0, 1); PG8_SCHED; PG8_LDA(At, 0, 0); PG8_STAGE(PG8_SA(1, 1), a1 + hstep, voffA);
;             PG8_WAIT_V(8); PG8_WAIT_L(0); PG8_BAR; PG8_MMA(0, 0, At, B0); PG8_MMA(0, 1, At, B1); PG8_BAR; PG8_SCHED;
;             PG8_LDA(At, 0, 1); PG8_STAGE(PG8_SB(0, 0), b2, voffB); PG8_STAGE(PG8_SB(0, 1), b2 + hstep, voffB); PG8_STAGE(PG8_SA(0, 0), a2, voffA);
.LBB0_274:
	s_add_i32 vcc_lo, s46, 2
	s_add_u32 s38, s48, 0x80
	s_addc_u32 s39, s49, 0
	s_add_i32 vcc_hi, 0, 0x10000
	s_cmp_eq_u32 s99, s46
	s_cselect_b32 s47, s81, s39
	s_cselect_b32 s46, s80, s38
	s_cselect_b32 s39, s83, s51
	s_cselect_b32 s38, s82, s50
	s_add_i32 s18, 0, 0x14000
	v_add_u32_e32 v142, vcc_hi, v245
	v_add_u32_e32 v158, s18, v245
	ds_read_b128 v[110:113], v142
	ds_read_b128 v[118:121], v142 offset:1024
	ds_read_b128 v[138:141], v142 offset:2048
	ds_read_b128 v[142:145], v142 offset:3072
	ds_read_b128 v[146:149], v158
	ds_read_b128 v[150:153], v158 offset:1024
	ds_read_b128 v[154:157], v158 offset:2048
	ds_read_b128 v[158:161], v158 offset:3072
	v_lshl_add_u64 v[210:211], s[48:49], 0, v[206:207]
	s_add_i32 m0, s92, 0xc000
	ds_read_b128 v[162:165], v247
	ds_read_b128 v[166:169], v247 offset:1024
	ds_read_b128 v[170:173], v247 offset:2048
	ds_read_b128 v[174:177], v247 offset:3072
	ds_read_b128 v[178:181], v247 offset:4096
	ds_read_b128 v[182:185], v247 offset:5120
	ds_read_b128 v[186:189], v247 offset:6144
	ds_read_b128 v[190:193], v247 offset:7168
	global_load_lds_dwordx4 v[210:211], off
	v_lshl_add_u64 v[210:211], s[48:49], 0, v[208:209]
	s_add_i32 m0, s92, 0xe000
	s_nop 0
	global_load_lds_dwordx4 v[210:211], off
	s_waitcnt vmcnt(8)
	s_waitcnt lgkmcnt(0)
	s_barrier
	s_setprio 1
	s_waitcnt lgkmcnt(0)
	v_mfma_f32_16x16x32_bf16 v[130:133], v[110:113], v[162:165], v[130:133]
	v_mfma_f32_16x16x32_bf16 v[134:137], v[138:141], v[162:165], v[134:137]
	v_mfma_f32_16x16x32_bf16 v[114:117], v[110:113], v[170:173], v[114:117]
	v_mfma_f32_16x16x32_bf16 v[106:109], v[138:141], v[170:173], v[106:109]
	v_mfma_f32_16x16x32_bf16 v[94:97], v[110:113], v[178:181], v[94:97]
	v_mfma_f32_16x16x32_bf16 v[90:93], v[138:141], v[178:181], v[90:93]
	v_mfma_f32_16x16x32_bf16 v[78:81], v[110:113], v[186:189], v[78:81]
	v_mfma_f32_16x16x32_bf16 v[74:77], v[138:141], v[186:189], v[74:77]
	v_mfma_f32_16x16x32_bf16 v[130:133], v[118:121], v[166:169], v[130:133]
	v_mfma_f32_16x16x32_bf16 v[134:137], v[142:145], v[166:169], v[134:137]
	v_mfma_f32_16x16x32_bf16 v[114:117], v[118:121], v[174:177], v[114:117]
	v_mfma_f32_16x16x32_bf16 v[106:109], v[142:145], v[174:177], v[106:109]
	v_mfma_f32_16x16x32_bf16 v[94:97], v[118:121], v[182:185], v[94:97]
	v_mfma_f32_16x16x32_bf16 v[90:93], v[142:145], v[182:185], v[90:93]
	v_mfma_f32_16x16x32_bf16 v[78:81], v[118:121], v[190:193], v[78:81]
	v_mfma_f32_16x16x32_bf16 v[74:77], v[142:145], v[190:193], v[74:77]
	v_mfma_f32_16x16x32_bf16 v[126:129], v[146:149], v[162:165], v[126:129]
	v_mfma_f32_16x16x32_bf16 v[122:125], v[154:157], v[162:165], v[122:125]
	v_mfma_f32_16x16x32_bf16 v[102:105], v[146:149], v[170:173], v[102:105]
	v_mfma_f32_16x16x32_bf16 v[98:101], v[154:157], v[170:173], v[98:101]
	v_mfma_f32_16x16x32_bf16 v[86:89], v[146:149], v[178:181], v[86:89]
	v_mfma_f32_16x16x32_bf16 v[82:85], v[154:157], v[178:181], v[82:85]
	v_mfma_f32_16x16x32_bf16 v[70:73], v[146:149], v[186:189], v[70:73]
	v_mfma_f32_16x16x32_bf16 v[66:69], v[154:157], v[186:189], v[66:69]
	v_mfma_f32_16x16x32_bf16 v[126:129], v[150:153], v[166:169], v[126:129]
	v_mfma_f32_16x16x32_bf16 v[122:125], v[158:161], v[166:169], v[122:125]
	v_mfma_f32_16x16x32_bf16 v[102:105], v[150:153], v[174:177], v[102:105]
	v_mfma_f32_16x16x32_bf16 v[98:101], v[158:161], v[174:177], v[98:101]
	v_mfma_f32_16x16x32_bf16 v[86:89], v[150:153], v[182:185], v[86:89]
	v_mfma_f32_16x16x32_bf16 v[82:85], v[158:161], v[182:185], v[82:85]
	v_mfma_f32_16x16x32_bf16 v[70:73], v[150:153], v[190:193], v[70:73]
	v_mfma_f32_16x16x32_bf16 v[66:69], v[158:161], v[190:193], v[66:69]
	s_setprio 0
	s_barrier
	s_add_i32 vcc_hi, vcc_hi, s6
	v_lshl_add_u64 v[210:211], s[38:39], 0, v[0:1]
	s_mov_b32 m0, vcc_hi
	ds_read_b128 v[162:165], v247 offset:16384
	ds_read_b128 v[166:169], v247 offset:17408
	ds_read_b128 v[170:173], v247 offset:18432
	ds_read_b128 v[174:177], v247 offset:19456
	ds_read_b128 v[178:181], v247 offset:20480
	ds_read_b128 v[182:185], v247 offset:21504
	ds_read_b128 v[186:189], v247 offset:22528
	ds_read_b128 v[190:193], v247 offset:23552
	global_load_lds_dwordx4 v[210:211], off
	s_add_i32 m0, vcc_hi, 0x2000
	v_lshl_add_u64 v[212:213], s[38:39], 0, v[204:205]
	s_add_u32 s38, s38, s58
	s_addc_u32 s39, s39, 0
	s_add_i32 s18, s18, s6
	global_load_lds_dwordx4 v[212:213], off
	v_lshl_add_u64 v[214:215], s[38:39], 0, v[0:1]
	s_mov_b32 m0, s18
	v_lshl_add_u64 v[216:217], s[38:39], 0, v[204:205]
	global_load_lds_dwordx4 v[214:215], off
	s_add_i32 m0, s18, 0x2000
	v_lshl_add_u64 v[218:219], s[46:47], 0, v[194:195]
	global_load_lds_dwordx4 v[216:217], off
	s_mov_b32 m0, s92
	v_lshl_add_u64 v[220:221], s[46:47], 0, v[202:203]
	global_load_lds_dwordx4 v[218:219], off
	s_mov_b32 m0, s93
	s_nop 0
	global_load_lds_dwordx4 v[220:221], off
	s_waitcnt vmcnt(8)
	s_waitcnt lgkmcnt(0)
	s_barrier
; #define PG8_STAGE(bufoff, gbase, voff) do { _Pragma("unroll") for (int _i = 0; _i < 2; ++_i) \
;         __builtin_amdgcn_global_load_lds((const unsigned*)((const char*)(gbase) + (voff)[_i]), (PG8_LAS unsigned*)(lds + (bufoff) + ldsw + _i * 8192), 16, 0, 0); } while (0)
; #define PG8_LDA(dst, b, h) do { _Pragma("unroll") for (int m = 0; m < 4; ++m) _Pragma("unroll") for (int k = 0; k < 2; ++k) dst[m][k] = *(const PG8_LAS bf16x8*)(lds + PG8_SA(b, h) + aoff + m * 2048 + k * 1024); } while (0)
; #define PG8_LDB(dst, b, h) do { _Pragma("unroll") for (int n = 0; n < 2; ++n) _Pragma("unroll") for (int k = 0; k < 2; ++k) dst[n][k] = *(const PG8_LAS bf16x8*)(lds + PG8_SB(b, h) + boff + n * 2048 + k * 1024); } while (0)
; #define PG8_MMA(ai, bj, At, Bt) do { __builtin_amdgcn_s_setprio(1); _Pragma("unroll") for (int m = 0; m < 4; ++m) _Pragma("unroll") for (int n = 0; n < 2; ++n) _Pragma("unroll") for (int k = 0; k < 2; ++k) \
;         acc[ai][bj][m][n] = __builtin_amdgcn_mfma_f32_16x16x32_bf16(Bt[n][k], At[m][k], acc[ai][bj][m][n], 0, 0, 0); __builtin_amdgcn_s_setprio(0); } while (0)
; #define PG8_WAIT_V(n) asm volatile("s_waitcnt vmcnt(" #n ")" ::: "memory")
; #define PG8_WAIT_L(n) asm volatile("s_waitcnt lgkmcnt(" #n ")" ::: "memory")
; #define PG8_BAR __builtin_amdgcn_s_barrier()
; #define PG8_SCHED __builtin_amdgcn_sched_barrier(0)
; template <class Epi, class Sched, bool ALIGN_EPI = false, bool SP2 = false>
; __device__ __forceinline__ void gemm_phase(PG8_LAS unsigned char* lds, const Gemm g, const Sched& S, const Epi& E) {
;     ...
;             PG8_WAIT_V(8); PG8_WAIT_L(0); PG8_BAR; PG8_MMA(1, 0, At, B0); PG8_MMA(1, 1, At, B1); PG8_BAR; PG8_SCHED;
;             PG8_LDB(B0, 1, 0); PG8_LDB(B1, 1, 1); PG8_SCHED; PG8_LDA(At, 1, 0); PG8_STAGE(PG8_SA(0, 1), a2 + hstep, voffA);
;             PG8_WAIT_V(8); PG8_WAIT_L(0); PG8_BAR; PG8_MMA(0, 0, At, B0); PG8_MMA(0, 1, At, B1); PG8_BAR; PG8_SCHED;
	s_setprio 1
	s_waitcnt lgkmcnt(0)
	v_mfma_f32_16x16x32_bf16 v[62:65], v[110:113], v[162:165], v[62:65]
	v_mfma_f32_16x16x32_bf16 v[58:61], v[138:141], v[162:165], v[58:61]
	v_mfma_f32_16x16x32_bf16 v[46:49], v[110:113], v[170:173], v[46:49]
	v_mfma_f32_16x16x32_bf16 v[42:45], v[138:141], v[170:173], v[42:45]
	v_mfma_f32_16x16x32_bf16 v[30:33], v[110:113], v[178:181], v[30:33]
	v_mfma_f32_16x16x32_bf16 v[26:29], v[138:141], v[178:181], v[26:29]
	v_mfma_f32_16x16x32_bf16 v[14:17], v[110:113], v[186:189], v[14:17]
	v_mfma_f32_16x16x32_bf16 v[10:13], v[138:141], v[186:189], v[10:13]
	v_mfma_f32_16x16x32_bf16 v[62:65], v[118:121], v[166:169], v[62:65]
	v_mfma_f32_16x16x32_bf16 v[58:61], v[142:145], v[166:169], v[58:61]
	v_mfma_f32_16x16x32_bf16 v[46:49], v[118:121], v[174:177], v[46:49]
	v_mfma_f32_16x16x32_bf16 v[42:45], v[142:145], v[174:177], v[42:45]
	v_mfma_f32_16x16x32_bf16 v[30:33], v[118:121], v[182:185], v[30:33]
	v_mfma_f32_16x16x32_bf16 v[26:29], v[142:145], v[182:185], v[26:29]
	v_mfma_f32_16x16x32_bf16 v[14:17], v[118:121], v[190:193], v[14:17]
	v_mfma_f32_16x16x32_bf16 v[10:13], v[142:145], v[190:193], v[10:13]
	v_mfma_f32_16x16x32_bf16 v[54:57], v[146:149], v[162:165], v[54:57]
	v_mfma_f32_16x16x32_bf16 v[50:53], v[154:157], v[162:165], v[50:53]
	v_mfma_f32_16x16x32_bf16 v[38:41], v[146:149], v[170:173], v[38:41]
	v_mfma_f32_16x16x32_bf16 v[34:37], v[154:157], v[170:173], v[34:37]
	v_mfma_f32_16x16x32_bf16 v[22:25], v[146:149], v[178:181], v[22:25]
	v_mfma_f32_16x16x32_bf16 v[18:21], v[154:157], v[178:181], v[18:21]
	v_mfma_f32_16x16x32_bf16 v[6:9], v[146:149], v[186:189], v[6:9]
	v_mfma_f32_16x16x32_bf16 v[2:5], v[154:157], v[186:189], v[2:5]
	v_mfma_f32_16x16x32_bf16 v[54:57], v[150:153], v[166:169], v[54:57]
	v_mfma_f32_16x16x32_bf16 v[50:53], v[158:161], v[166:169], v[50:53]
	v_mfma_f32_16x16x32_bf16 v[38:41], v[150:153], v[174:177], v[38:41]
	v_mfma_f32_16x16x32_bf16 v[34:37], v[158:161], v[174:177], v[34:37]
	v_mfma_f32_16x16x32_bf16 v[22:25], v[150:153], v[182:185], v[22:25]
	v_mfma_f32_16x16x32_bf16 v[18:21], v[158:161], v[182:185], v[18:21]
	v_mfma_f32_16x16x32_bf16 v[6:9], v[150:153], v[190:193], v[6:9]
	v_mfma_f32_16x16x32_bf16 v[2:5], v[158:161], v[190:193], v[2:5]
	s_setprio 0
	s_barrier
	s_add_i32 s18, 0, 0x18000
	s_add_i32 vcc_hi, 0, 0x1c000
	v_add_u32_e32 v142, s18, v245
	v_add_u32_e32 v158, vcc_hi, v245
	ds_read_b128 v[110:113], v142
	ds_read_b128 v[118:121], v142 offset:1024
	ds_read_b128 v[138:141], v142 offset:2048
	ds_read_b128 v[142:145], v142 offset:3072
	ds_read_b128 v[146:149], v158
	ds_read_b128 v[150:153], v158 offset:1024
	ds_read_b128 v[154:157], v158 offset:2048
	ds_read_b128 v[158:161], v158 offset:3072
	s_add_u32 s38, s46, s58
	s_addc_u32 s39, s47, 0
	s_mov_b32 m0, s94
	v_lshl_add_u64 v[222:223], s[38:39], 0, v[194:195]
	ds_read_b128 v[162:165], v247 offset:32768
	ds_read_b128 v[166:169], v247 offset:33792
	ds_read_b128 v[170:173], v247 offset:34816
	ds_read_b128 v[174:177], v247 offset:35840
	ds_read_b128 v[178:181], v247 offset:36864
	ds_read_b128 v[182:185], v247 offset:37888
	ds_read_b128 v[186:189], v247 offset:38912
	ds_read_b128 v[190:193], v247 offset:39936
	global_load_lds_dwordx4 v[222:223], off
	v_lshl_add_u64 v[222:223], s[38:39], 0, v[202:203]
	s_mov_b32 m0, s95
	s_nop 0
	global_load_lds_dwordx4 v[222:223], off
	s_waitcnt vmcnt(8)
	s_waitcnt lgkmcnt(0)
	s_barrier
	s_setprio 1
	s_waitcnt lgkmcnt(0)
	v_mfma_f32_16x16x32_bf16 v[130:133], v[110:113], v[162:165], v[130:133]
	v_mfma_f32_16x16x32_bf16 v[134:137], v[138:141], v[162:165], v[134:137]
	v_mfma_f32_16x16x32_bf16 v[114:117], v[110:113], v[170:173], v[114:117]
	v_mfma_f32_16x16x32_bf16 v[106:109], v[138:141], v[170:173], v[106:109]
	v_mfma_f32_16x16x32_bf16 v[94:97], v[110:113], v[178:181], v[94:97]
	v_mfma_f32_16x16x32_bf16 v[90:93], v[138:141], v[178:181], v[90:93]
	v_mfma_f32_16x16x32_bf16 v[78:81], v[110:113], v[186:189], v[78:81]
	v_mfma_f32_16x16x32_bf16 v[74:77], v[138:141], v[186:189], v[74:77]
	v_mfma_f32_16x16x32_bf16 v[130:133], v[118:121], v[166:169], v[130:133]
	v_mfma_f32_16x16x32_bf16 v[134:137], v[142:145], v[166:169], v[134:137]
	v_mfma_f32_16x16x32_bf16 v[114:117], v[118:121], v[174:177], v[114:117]
	v_mfma_f32_16x16x32_bf16 v[106:109], v[142:145], v[174:177], v[106:109]
	v_mfma_f32_16x16x32_bf16 v[94:97], v[118:121], v[182:185], v[94:97]
	v_mfma_f32_16x16x32_bf16 v[90:93], v[142:145], v[182:185], v[90:93]
	v_mfma_f32_16x16x32_bf16 v[78:81], v[118:121], v[190:193], v[78:81]
	v_mfma_f32_16x16x32_bf16 v[74:77], v[142:145], v[190:193], v[74:77]
	v_mfma_f32_16x16x32_bf16 v[126:129], v[146:149], v[162:165], v[126:129]
	v_mfma_f32_16x16x32_bf16 v[122:125], v[154:157], v[162:165], v[122:125]
	v_mfma_f32_16x16x32_bf16 v[102:105], v[146:149], v[170:173], v[102:105]
	v_mfma_f32_16x16x32_bf16 v[98:101], v[154:157], v[170:173], v[98:101]
	v_mfma_f32_16x16x32_bf16 v[86:89], v[146:149], v[178:181], v[86:89]
	v_mfma_f32_16x16x32_bf16 v[82:85], v[154:157], v[178:181], v[82:85]
	v_mfma_f32_16x16x32_bf16 v[70:73], v[146:149], v[186:189], v[70:73]
	v_mfma_f32_16x16x32_bf16 v[66:69], v[154:157], v[186:189], v[66:69]
	v_mfma_f32_16x16x32_bf16 v[126:129], v[150:153], v[166:169], v[126:129]
	v_mfma_f32_16x16x32_bf16 v[122:125], v[158:161], v[166:169], v[122:125]
	v_mfma_f32_16x16x32_bf16 v[102:105], v[150:153], v[174:177], v[102:105]
	v_mfma_f32_16x16x32_bf16 v[98:101], v[158:161], v[174:177], v[98:101]
	v_mfma_f32_16x16x32_bf16 v[86:89], v[150:153], v[182:185], v[86:89]
	v_mfma_f32_16x16x32_bf16 v[82:85], v[158:161], v[182:185], v[82:85]
	v_mfma_f32_16x16x32_bf16 v[70:73], v[150:153], v[190:193], v[70:73]
	v_mfma_f32_16x16x32_bf16 v[66:69], v[158:161], v[190:193], v[66:69]
	s_setprio 0
	s_barrier
; #define PG8_STAGE(bufoff, gbase, voff) do { _Pragma("unroll") for (int _i = 0; _i < 2; ++_i) \
;         __builtin_amdgcn_global_load_lds((const unsigned*)((const char*)(gbase) + (voff)[_i]), (PG8_LAS unsigned*)(lds + (bufoff) + ldsw + _i * 8192), 16, 0, 0); } while (0)
; #define PG8_LDA(dst, b, h) do { _Pragma("unroll") for (int m = 0; m < 4; ++m) _Pragma("unroll") for (int k = 0; k < 2; ++k) dst[m][k] = *(const PG8_LAS bf16x8*)(lds + PG8_SA(b, h) + aoff + m * 2048 + k * 1024); } while (0)
; #define PG8_MMA(ai, bj, At, Bt) do { __builtin_amdgcn_s_setprio(1); _Pragma("unroll") for (int m = 0; m < 4; ++m) _Pragma("unroll") for (int n = 0; n < 2; ++n) _Pragma("unroll") for (int k = 0; k < 2; ++k) \
;         acc[ai][bj][m][n] = __builtin_amdgcn_mfma_f32_16x16x32_bf16(Bt[n][k], At[m][k], acc[ai][bj][m][n], 0, 0, 0); __builtin_amdgcn_s_setprio(0); } while (0)
; #define PG8_WAIT_V(n) asm volatile("s_waitcnt vmcnt(" #n ")" ::: "memory")
; #define PG8_WAIT_L(n) asm volatile("s_waitcnt lgkmcnt(" #n ")" ::: "memory")
; #define PG8_BAR __builtin_amdgcn_s_barrier()
; #define PG8_SCHED __builtin_amdgcn_sched_barrier(0)
; template <class Epi, class Sched, bool ALIGN_EPI = false, bool SP2 = false>
; __device__ __forceinline__ void gemm_phase(PG8_LAS unsigned char* lds, const Gemm g, const Sched& S, const Epi& E) {
;     ...
;         for (int t = 0; t < nt; t += 2) {
;     ...
;             PG8_LDA(At, 1, 1); PG8_STAGE(PG8_SB(1, 0), b3, voffB); PG8_STAGE(PG8_SB(1, 1), b3 + hstep, voffB); PG8_STAGE(PG8_SA(1, 0), a3, voffA);
;             PG8_WAIT_V(8); PG8_WAIT_L(0); PG8_BAR; PG8_MMA(1, 0, At, B0); PG8_MMA(1, 1, At, B1); PG8_BAR; PG8_SCHED;
	s_add_i32 s18, s18, s6
	v_lshl_add_u64 v[210:211], v[210:211], 0, s[30:31]
	s_mov_b32 m0, s18
	ds_read_b128 v[162:165], v247 offset:49152
	ds_read_b128 v[166:169], v247 offset:50176
	ds_read_b128 v[170:173], v247 offset:51200
	ds_read_b128 v[174:177], v247 offset:52224
	ds_read_b128 v[178:181], v247 offset:53248
	ds_read_b128 v[182:185], v247 offset:54272
	ds_read_b128 v[186:189], v247 offset:55296
	ds_read_b128 v[190:193], v247 offset:56320
	global_load_lds_dwordx4 v[210:211], off
	v_lshl_add_u64 v[210:211], v[212:213], 0, s[30:31]
	s_add_i32 m0, s18, 0x2000
	s_add_i32 s18, vcc_hi, s6
	global_load_lds_dwordx4 v[210:211], off
	v_lshl_add_u64 v[210:211], v[214:215], 0, s[30:31]
	s_mov_b32 m0, s18
	s_nop 0
	global_load_lds_dwordx4 v[210:211], off
	v_lshl_add_u64 v[210:211], v[216:217], 0, s[30:31]
	s_add_i32 m0, s18, 0x2000
	s_nop 0
	global_load_lds_dwordx4 v[210:211], off
	v_lshl_add_u64 v[210:211], v[218:219], 0, s[30:31]
	s_mov_b32 m0, s97
	s_nop 0
	global_load_lds_dwordx4 v[210:211], off
	v_lshl_add_u64 v[210:211], v[220:221], 0, s[30:31]
	s_mov_b32 m0, s98
	s_nop 0
	global_load_lds_dwordx4 v[210:211], off
	s_waitcnt vmcnt(8)
	s_waitcnt lgkmcnt(0)
	s_barrier
	s_setprio 1
	s_waitcnt lgkmcnt(0)
	v_mfma_f32_16x16x32_bf16 v[62:65], v[110:113], v[162:165], v[62:65]
	v_mfma_f32_16x16x32_bf16 v[58:61], v[138:141], v[162:165], v[58:61]
	v_mfma_f32_16x16x32_bf16 v[46:49], v[110:113], v[170:173], v[46:49]
	v_mfma_f32_16x16x32_bf16 v[42:45], v[138:141], v[170:173], v[42:45]
	v_mfma_f32_16x16x32_bf16 v[30:33], v[110:113], v[178:181], v[30:33]
	v_mfma_f32_16x16x32_bf16 v[26:29], v[138:141], v[178:181], v[26:29]
	v_mfma_f32_16x16x32_bf16 v[14:17], v[110:113], v[186:189], v[14:17]
	v_mfma_f32_16x16x32_bf16 v[10:13], v[138:141], v[186:189], v[10:13]
	v_mfma_f32_16x16x32_bf16 v[62:65], v[118:121], v[166:169], v[62:65]
	v_mfma_f32_16x16x32_bf16 v[58:61], v[142:145], v[166:169], v[58:61]
	v_mfma_f32_16x16x32_bf16 v[46:49], v[118:121], v[174:177], v[46:49]
	v_mfma_f32_16x16x32_bf16 v[42:45], v[142:145], v[174:177], v[42:45]
	v_mfma_f32_16x16x32_bf16 v[30:33], v[118:121], v[182:185], v[30:33]
	v_mfma_f32_16x16x32_bf16 v[26:29], v[142:145], v[182:185], v[26:29]
	v_mfma_f32_16x16x32_bf16 v[14:17], v[118:121], v[190:193], v[14:17]
	v_mfma_f32_16x16x32_bf16 v[10:13], v[142:145], v[190:193], v[10:13]
	v_mfma_f32_16x16x32_bf16 v[54:57], v[146:149], v[162:165], v[54:57]
	v_mfma_f32_16x16x32_bf16 v[50:53], v[154:157], v[162:165], v[50:53]
	v_mfma_f32_16x16x32_bf16 v[38:41], v[146:149], v[170:173], v[38:41]
	v_mfma_f32_16x16x32_bf16 v[34:37], v[154:157], v[170:173], v[34:37]
	v_mfma_f32_16x16x32_bf16 v[22:25], v[146:149], v[178:181], v[22:25]
	v_mfma_f32_16x16x32_bf16 v[18:21], v[154:157], v[178:181], v[18:21]
	v_mfma_f32_16x16x32_bf16 v[6:9], v[146:149], v[186:189], v[6:9]
	v_mfma_f32_16x16x32_bf16 v[2:5], v[154:157], v[186:189], v[2:5]
	v_mfma_f32_16x16x32_bf16 v[54:57], v[150:153], v[166:169], v[54:57]
	v_mfma_f32_16x16x32_bf16 v[50:53], v[158:161], v[166:169], v[50:53]
	v_mfma_f32_16x16x32_bf16 v[38:41], v[150:153], v[174:177], v[38:41]
	v_mfma_f32_16x16x32_bf16 v[34:37], v[158:161], v[174:177], v[34:37]
	v_mfma_f32_16x16x32_bf16 v[22:25], v[150:153], v[182:185], v[22:25]
	v_mfma_f32_16x16x32_bf16 v[18:21], v[158:161], v[182:185], v[18:21]
	v_mfma_f32_16x16x32_bf16 v[6:9], v[150:153], v[190:193], v[6:9]
	v_mfma_f32_16x16x32_bf16 v[2:5], v[158:161], v[190:193], v[2:5]
	s_setprio 0
	s_barrier
	s_add_u32 s48, s48, 0x100
	s_addc_u32 s49, s49, 0
	s_add_u32 s50, s50, 0x100
	s_addc_u32 s51, s51, 0
	s_cmp_ge_u32 vcc_lo, s96
	s_mov_b32 s46, vcc_lo
	s_cbranch_scc0 .LBB0_274
	s_and_b64 vcc, exec, s[72:73]
	s_cbranch_vccz .LBB0_277
	s_barrier

; #define PG8_STAGE(bufoff, gbase, voff) do { _Pragma("unroll") for (int _i = 0; _i < 2; ++_i) \
;         __builtin_amdgcn_global_load_lds((const unsigned*)((const char*)(gbase) + (voff)[_i]), (PG8_LAS unsigned*)(lds + (bufoff) + ldsw + _i * 8192), 16, 0, 0); } while (0)
; #define PG8_LDA(dst, b, h) do { _Pragma("unroll") for (int m = 0; m < 4; ++m) _Pragma("unroll") for (int k = 0; k < 2; ++k) dst[m][k] = *(const PG8_LAS bf16x8*)(lds + PG8_SA(b, h) + aoff + m * 2048 + k * 1024); } while (0)
; #define PG8_LDB(dst, b, h) do { _Pragma("unroll") for (int n = 0; n < 2; ++n) _Pragma("unroll") for (int k = 0; k < 2; ++k) dst[n][k] = *(const PG8_LAS bf16x8*)(lds + PG8_SB(b, h) + boff + n * 2048 + k * 1024); } while (0)
; #define PG8_MMA(ai, bj, At, Bt) do { __builtin_amdgcn_s_setprio(1); _Pragma("unroll") for (int m = 0; m < 4; ++m) _Pragma("unroll") for (int n = 0; n < 2; ++n) _Pragma("unroll") for (int k = 0; k < 2; ++k) \
;         acc[ai][bj][m][n] = __builtin_amdgcn_mfma_f32_16x16x32_bf16(Bt[n][k], At[m][k], acc[ai][bj][m][n], 0, 0, 0); __builtin_amdgcn_s_setprio(0); } while (0)
; #define PG8_WAIT_V(n) asm volatile("s_waitcnt vmcnt(" #n ")" ::: "memory")
; #define PG8_WAIT_L(n) asm volatile("s_waitcnt lgkmcnt(" #n ")" ::: "memory")
; #define PG8_BAR __builtin_amdgcn_s_barrier()
; #define PG8_SCHED __builtin_amdgcn_sched_barrier(0)
; template <class Epi, class Sched, bool ALIGN_EPI = false, bool SP2 = false>
; __device__ __forceinline__ void gemm_phase(PG8_LAS unsigned char* lds, const Gemm g, const Sched& S, const Epi& E) {
;     ...
;         for (int t = 0; t < nt; t += 2) {
;             const bool last = (t == nt - 2);
;             const char* a1 = cA + (size_t)(t + 1) * kstep;
;             const char* a2 = last ? nA : cA + (size_t)(t + 2) * kstep; const char* b2 = last ? nB : cB + (size_t)(t + 2) * kstep;
;             const char* a3 = a2 + kstep; const char* b3 = b2 + kstep;
;             if (last && has_next) S.a_ready(nxt);
;             if constexpr (SP2) {
;             PG8_LDB(B0, 0, 0); PG8_LDB(B1, 0, 1); PG8_SCHED; PG8_LDA(At, 0, 0); PG8_STAGE(PG8_SA(1, 1), a1 + hstep, voffA);
;             PG8_WAIT_V(8); PG8_WAIT_L(0); PG8_BAR; PG8_MMA(0, 0, At, B0); PG8_MMA(0, 1, At, B1); PG8_BAR; PG8_SCHED;
;             PG8_LDA(At, 0, 1); PG8_STAGE(PG8_SB(0, 0), b2, voffB); PG8_STAGE(PG8_SB(0, 1), b2 + hstep, voffB); PG8_STAGE(PG8_SA(0, 0), a2, voffA);
.LBB0_408:
	s_add_u32 s38, s48, 0xfffc0080
	s_addc_u32 s39, s49, -1
	s_add_i32 s85, 0, 0x10000
	s_cmp_eq_u32 s84, 12
	s_cselect_b32 s73, s21, s39
	s_cselect_b32 s72, s27, s38
	v_add_u32_e32 v0, s85, v167
	s_cselect_b32 s47, s29, s69
	s_cselect_b32 s46, s33, s53
	s_add_i32 s38, 0, 0x14000
	ds_read_b128 v[142:145], v0
	ds_read_b128 v[146:149], v0 offset:1024
	ds_read_b128 v[150:153], v0 offset:2048
	ds_read_b128 v[154:157], v0 offset:3072
	v_add_u32_e32 v0, s38, v167
	ds_read_b128 v[158:161], v0
	ds_read_b128 v[162:165], v0 offset:1024
	ds_read_b128 v[172:175], v0 offset:2048
	ds_read_b128 v[176:179], v0 offset:3072
	v_lshl_add_u64 v[218:219], s[48:49], 0, v[138:139]
	s_add_i32 m0, s76, 0xc000
	ds_read_b128 v[180:183], v170
	ds_read_b128 v[184:187], v170 offset:1024
	ds_read_b128 v[188:191], v170 offset:2048
	ds_read_b128 v[192:195], v170 offset:3072
	ds_read_b128 v[202:205], v170 offset:4096
	ds_read_b128 v[206:209], v170 offset:5120
	ds_read_b128 v[210:213], v170 offset:6144
	ds_read_b128 v[214:217], v170 offset:7168
	global_load_lds_dwordx4 v[218:219], off
	v_lshl_add_u64 v[218:219], s[48:49], 0, v[140:141]
	s_add_i32 m0, s76, 0xe000
	s_nop 0
	global_load_lds_dwordx4 v[218:219], off
	s_waitcnt vmcnt(8)
	s_waitcnt lgkmcnt(0)
	s_barrier
	s_setprio 1
	s_waitcnt lgkmcnt(0)
	v_mfma_f32_16x16x32_bf16 v[122:125], v[142:145], v[180:183], v[122:125]
	v_mfma_f32_16x16x32_bf16 v[126:129], v[150:153], v[180:183], v[126:129]
	v_mfma_f32_16x16x32_bf16 v[106:109], v[142:145], v[188:191], v[106:109]
	v_mfma_f32_16x16x32_bf16 v[110:113], v[150:153], v[188:191], v[110:113]
	v_mfma_f32_16x16x32_bf16 v[90:93], v[142:145], v[202:205], v[90:93]
	v_mfma_f32_16x16x32_bf16 v[94:97], v[150:153], v[202:205], v[94:97]
	v_mfma_f32_16x16x32_bf16 v[74:77], v[142:145], v[210:213], v[74:77]
	v_mfma_f32_16x16x32_bf16 v[78:81], v[150:153], v[210:213], v[78:81]
	v_mfma_f32_16x16x32_bf16 v[122:125], v[146:149], v[184:187], v[122:125]
	v_mfma_f32_16x16x32_bf16 v[126:129], v[154:157], v[184:187], v[126:129]
	v_mfma_f32_16x16x32_bf16 v[106:109], v[146:149], v[192:195], v[106:109]
	v_mfma_f32_16x16x32_bf16 v[110:113], v[154:157], v[192:195], v[110:113]
	v_mfma_f32_16x16x32_bf16 v[90:93], v[146:149], v[206:209], v[90:93]
	v_mfma_f32_16x16x32_bf16 v[94:97], v[154:157], v[206:209], v[94:97]
	v_mfma_f32_16x16x32_bf16 v[74:77], v[146:149], v[214:217], v[74:77]
	v_mfma_f32_16x16x32_bf16 v[78:81], v[154:157], v[214:217], v[78:81]
	v_mfma_f32_16x16x32_bf16 v[114:117], v[158:161], v[180:183], v[114:117]
	v_mfma_f32_16x16x32_bf16 v[118:121], v[172:175], v[180:183], v[118:121]
	v_mfma_f32_16x16x32_bf16 v[98:101], v[158:161], v[188:191], v[98:101]
	v_mfma_f32_16x16x32_bf16 v[102:105], v[172:175], v[188:191], v[102:105]
	v_mfma_f32_16x16x32_bf16 v[82:85], v[158:161], v[202:205], v[82:85]
	v_mfma_f32_16x16x32_bf16 v[86:89], v[172:175], v[202:205], v[86:89]
	v_mfma_f32_16x16x32_bf16 v[66:69], v[158:161], v[210:213], v[66:69]
	v_mfma_f32_16x16x32_bf16 v[70:73], v[172:175], v[210:213], v[70:73]
	v_mfma_f32_16x16x32_bf16 v[114:117], v[162:165], v[184:187], v[114:117]
	v_mfma_f32_16x16x32_bf16 v[118:121], v[176:179], v[184:187], v[118:121]
	v_mfma_f32_16x16x32_bf16 v[98:101], v[162:165], v[192:195], v[98:101]
	v_mfma_f32_16x16x32_bf16 v[102:105], v[176:179], v[192:195], v[102:105]
	v_mfma_f32_16x16x32_bf16 v[82:85], v[162:165], v[206:209], v[82:85]
	v_mfma_f32_16x16x32_bf16 v[86:89], v[176:179], v[206:209], v[86:89]
	v_mfma_f32_16x16x32_bf16 v[66:69], v[162:165], v[214:217], v[66:69]
	v_mfma_f32_16x16x32_bf16 v[70:73], v[176:179], v[214:217], v[70:73]
	s_setprio 0
	s_barrier
	s_add_i32 s39, s85, s75
	v_lshl_add_u64 v[218:219], s[46:47], 0, v[134:135]
	s_mov_b32 m0, s39
	ds_read_b128 v[180:183], v170 offset:16384
	ds_read_b128 v[184:187], v170 offset:17408
	ds_read_b128 v[188:191], v170 offset:18432
	ds_read_b128 v[192:195], v170 offset:19456
	ds_read_b128 v[202:205], v170 offset:20480
	ds_read_b128 v[206:209], v170 offset:21504
	ds_read_b128 v[210:213], v170 offset:22528
	ds_read_b128 v[214:217], v170 offset:23552
	global_load_lds_dwordx4 v[218:219], off
	s_add_i32 m0, s39, 0x2000
	s_add_u32 s92, s46, 0x40000
	v_lshl_add_u64 v[220:221], s[46:47], 0, v[130:131]
	s_addc_u32 s93, s47, 0
	s_add_i32 s38, s38, s75
	global_load_lds_dwordx4 v[220:221], off
	v_lshl_add_u64 v[222:223], s[92:93], 0, v[134:135]
	s_mov_b32 m0, s38
	v_lshl_add_u64 v[224:225], s[72:73], 0, v[132:133]
	global_load_lds_dwordx4 v[222:223], off
	v_lshl_add_u64 v[222:223], s[92:93], 0, v[130:131]
	s_add_i32 m0, s38, 0x2000
	s_nop 0
	global_load_lds_dwordx4 v[222:223], off
	v_lshl_add_u64 v[222:223], s[72:73], 0, v[136:137]
	s_mov_b32 m0, s76
	s_nop 0
	global_load_lds_dwordx4 v[222:223], off
	s_mov_b32 m0, s77
	s_nop 0
	global_load_lds_dwordx4 v[224:225], off
	s_waitcnt vmcnt(8)
	s_waitcnt lgkmcnt(0)
	s_barrier
; #define PG8_STAGE(bufoff, gbase, voff) do { _Pragma("unroll") for (int _i = 0; _i < 2; ++_i) \
;         __builtin_amdgcn_global_load_lds((const unsigned*)((const char*)(gbase) + (voff)[_i]), (PG8_LAS unsigned*)(lds + (bufoff) + ldsw + _i * 8192), 16, 0, 0); } while (0)
; #define PG8_LDA(dst, b, h) do { _Pragma("unroll") for (int m = 0; m < 4; ++m) _Pragma("unroll") for (int k = 0; k < 2; ++k) dst[m][k] = *(const PG8_LAS bf16x8*)(lds + PG8_SA(b, h) + aoff + m * 2048 + k * 1024); } while (0)
; #define PG8_LDB(dst, b, h) do { _Pragma("unroll") for (int n = 0; n < 2; ++n) _Pragma("unroll") for (int k = 0; k < 2; ++k) dst[n][k] = *(const PG8_LAS bf16x8*)(lds + PG8_SB(b, h) + boff + n * 2048 + k * 1024); } while (0)
; #define PG8_MMA(ai, bj, At, Bt) do { __builtin_amdgcn_s_setprio(1); _Pragma("unroll") for (int m = 0; m < 4; ++m) _Pragma("unroll") for (int n = 0; n < 2; ++n) _Pragma("unroll") for (int k = 0; k < 2; ++k) \
;         acc[ai][bj][m][n] = __builtin_amdgcn_mfma_f32_16x16x32_bf16(Bt[n][k], At[m][k], acc[ai][bj][m][n], 0, 0, 0); __builtin_amdgcn_s_setprio(0); } while (0)
; #define PG8_WAIT_V(n) asm volatile("s_waitcnt vmcnt(" #n ")" ::: "memory")
; #define PG8_WAIT_L(n) asm volatile("s_waitcnt lgkmcnt(" #n ")" ::: "memory")
; #define PG8_BAR __builtin_amdgcn_s_barrier()
; #define PG8_SCHED __builtin_amdgcn_sched_barrier(0)
; template <class Epi, class Sched, bool ALIGN_EPI = false, bool SP2 = false>
; __device__ __forceinline__ void gemm_phase(PG8_LAS unsigned char* lds, const Gemm g, const Sched& S, const Epi& E) {
;     ...
;             PG8_WAIT_V(8); PG8_WAIT_L(0); PG8_BAR; PG8_MMA(1, 0, At, B0); PG8_MMA(1, 1, At, B1); PG8_BAR; PG8_SCHED;
;             PG8_LDB(B0, 1, 0); PG8_LDB(B1, 1, 1); PG8_SCHED; PG8_LDA(At, 1, 0); PG8_STAGE(PG8_SA(0, 1), a2 + hstep, voffA);
;             PG8_WAIT_V(8); PG8_WAIT_L(0); PG8_BAR; PG8_MMA(0, 0, At, B0); PG8_MMA(0, 1, At, B1); PG8_BAR; PG8_SCHED;
	s_setprio 1
	s_waitcnt lgkmcnt(0)
	v_mfma_f32_16x16x32_bf16 v[58:61], v[142:145], v[180:183], v[58:61]
	v_mfma_f32_16x16x32_bf16 v[62:65], v[150:153], v[180:183], v[62:65]
	v_mfma_f32_16x16x32_bf16 v[42:45], v[142:145], v[188:191], v[42:45]
	v_mfma_f32_16x16x32_bf16 v[46:49], v[150:153], v[188:191], v[46:49]
	v_mfma_f32_16x16x32_bf16 v[26:29], v[142:145], v[202:205], v[26:29]
	v_mfma_f32_16x16x32_bf16 v[30:33], v[150:153], v[202:205], v[30:33]
	v_mfma_f32_16x16x32_bf16 v[10:13], v[142:145], v[210:213], v[10:13]
	v_mfma_f32_16x16x32_bf16 v[14:17], v[150:153], v[210:213], v[14:17]
	v_mfma_f32_16x16x32_bf16 v[58:61], v[146:149], v[184:187], v[58:61]
	v_mfma_f32_16x16x32_bf16 v[62:65], v[154:157], v[184:187], v[62:65]
	v_mfma_f32_16x16x32_bf16 v[42:45], v[146:149], v[192:195], v[42:45]
	v_mfma_f32_16x16x32_bf16 v[46:49], v[154:157], v[192:195], v[46:49]
	v_mfma_f32_16x16x32_bf16 v[26:29], v[146:149], v[206:209], v[26:29]
	v_mfma_f32_16x16x32_bf16 v[30:33], v[154:157], v[206:209], v[30:33]
	v_mfma_f32_16x16x32_bf16 v[10:13], v[146:149], v[214:217], v[10:13]
	v_mfma_f32_16x16x32_bf16 v[14:17], v[154:157], v[214:217], v[14:17]
	v_mfma_f32_16x16x32_bf16 v[50:53], v[158:161], v[180:183], v[50:53]
	v_mfma_f32_16x16x32_bf16 v[54:57], v[172:175], v[180:183], v[54:57]
	v_mfma_f32_16x16x32_bf16 v[34:37], v[158:161], v[188:191], v[34:37]
	v_mfma_f32_16x16x32_bf16 v[38:41], v[172:175], v[188:191], v[38:41]
	v_mfma_f32_16x16x32_bf16 v[18:21], v[158:161], v[202:205], v[18:21]
	v_mfma_f32_16x16x32_bf16 v[22:25], v[172:175], v[202:205], v[22:25]
	v_mfma_f32_16x16x32_bf16 v[2:5], v[158:161], v[210:213], v[2:5]
	v_mfma_f32_16x16x32_bf16 v[6:9], v[172:175], v[210:213], v[6:9]
	v_mfma_f32_16x16x32_bf16 v[50:53], v[162:165], v[184:187], v[50:53]
	v_mfma_f32_16x16x32_bf16 v[54:57], v[176:179], v[184:187], v[54:57]
	v_mfma_f32_16x16x32_bf16 v[34:37], v[162:165], v[192:195], v[34:37]
	v_mfma_f32_16x16x32_bf16 v[38:41], v[176:179], v[192:195], v[38:41]
	v_mfma_f32_16x16x32_bf16 v[18:21], v[162:165], v[206:209], v[18:21]
	v_mfma_f32_16x16x32_bf16 v[22:25], v[176:179], v[206:209], v[22:25]
	v_mfma_f32_16x16x32_bf16 v[2:5], v[162:165], v[214:217], v[2:5]
	v_mfma_f32_16x16x32_bf16 v[6:9], v[176:179], v[214:217], v[6:9]
	s_setprio 0
	s_barrier
	s_add_i32 s38, 0, 0x18000
	v_add_u32_e32 v0, s38, v167
	s_add_i32 s39, 0, 0x1c000
	ds_read_b128 v[142:145], v0
	ds_read_b128 v[146:149], v0 offset:1024
	ds_read_b128 v[150:153], v0 offset:2048
	ds_read_b128 v[154:157], v0 offset:3072
	v_add_u32_e32 v0, s39, v167
	ds_read_b128 v[158:161], v0
	ds_read_b128 v[162:165], v0 offset:1024
	ds_read_b128 v[172:175], v0 offset:2048
	ds_read_b128 v[176:179], v0 offset:3072
	s_add_u32 s72, s72, 0x40000
	s_addc_u32 s73, s73, 0
	s_mov_b32 m0, s78
	v_lshl_add_u64 v[226:227], s[72:73], 0, v[136:137]
	ds_read_b128 v[180:183], v170 offset:32768
	ds_read_b128 v[184:187], v170 offset:33792
	ds_read_b128 v[188:191], v170 offset:34816
	ds_read_b128 v[192:195], v170 offset:35840
	ds_read_b128 v[202:205], v170 offset:36864
	ds_read_b128 v[206:209], v170 offset:37888
	ds_read_b128 v[210:213], v170 offset:38912
	ds_read_b128 v[214:217], v170 offset:39936
	global_load_lds_dwordx4 v[226:227], off
	v_lshl_add_u64 v[226:227], s[72:73], 0, v[132:133]
	s_mov_b32 m0, s79
	s_nop 0
	global_load_lds_dwordx4 v[226:227], off
	s_waitcnt vmcnt(8)
	s_waitcnt lgkmcnt(0)
	s_barrier
	s_setprio 1
	s_waitcnt lgkmcnt(0)
	v_mfma_f32_16x16x32_bf16 v[122:125], v[142:145], v[180:183], v[122:125]
	v_mfma_f32_16x16x32_bf16 v[126:129], v[150:153], v[180:183], v[126:129]
	v_mfma_f32_16x16x32_bf16 v[106:109], v[142:145], v[188:191], v[106:109]
	v_mfma_f32_16x16x32_bf16 v[110:113], v[150:153], v[188:191], v[110:113]
	v_mfma_f32_16x16x32_bf16 v[90:93], v[142:145], v[202:205], v[90:93]
	v_mfma_f32_16x16x32_bf16 v[94:97], v[150:153], v[202:205], v[94:97]
	v_mfma_f32_16x16x32_bf16 v[74:77], v[142:145], v[210:213], v[74:77]
	v_mfma_f32_16x16x32_bf16 v[78:81], v[150:153], v[210:213], v[78:81]
	v_mfma_f32_16x16x32_bf16 v[122:125], v[146:149], v[184:187], v[122:125]
	v_mfma_f32_16x16x32_bf16 v[126:129], v[154:157], v[184:187], v[126:129]
	v_mfma_f32_16x16x32_bf16 v[106:109], v[146:149], v[192:195], v[106:109]
	v_mfma_f32_16x16x32_bf16 v[110:113], v[154:157], v[192:195], v[110:113]
	v_mfma_f32_16x16x32_bf16 v[90:93], v[146:149], v[206:209], v[90:93]
	v_mfma_f32_16x16x32_bf16 v[94:97], v[154:157], v[206:209], v[94:97]
	v_mfma_f32_16x16x32_bf16 v[74:77], v[146:149], v[214:217], v[74:77]
	v_mfma_f32_16x16x32_bf16 v[78:81], v[154:157], v[214:217], v[78:81]
	v_mfma_f32_16x16x32_bf16 v[114:117], v[158:161], v[180:183], v[114:117]
	v_mfma_f32_16x16x32_bf16 v[118:121], v[172:175], v[180:183], v[118:121]
	v_mfma_f32_16x16x32_bf16 v[98:101], v[158:161], v[188:191], v[98:101]
	v_mfma_f32_16x16x32_bf16 v[102:105], v[172:175], v[188:191], v[102:105]
	v_mfma_f32_16x16x32_bf16 v[82:85], v[158:161], v[202:205], v[82:85]
	v_mfma_f32_16x16x32_bf16 v[86:89], v[172:175], v[202:205], v[86:89]
	v_mfma_f32_16x16x32_bf16 v[66:69], v[158:161], v[210:213], v[66:69]
	v_mfma_f32_16x16x32_bf16 v[70:73], v[172:175], v[210:213], v[70:73]
	v_mfma_f32_16x16x32_bf16 v[114:117], v[162:165], v[184:187], v[114:117]
	v_mfma_f32_16x16x32_bf16 v[118:121], v[176:179], v[184:187], v[118:121]
	v_mfma_f32_16x16x32_bf16 v[98:101], v[162:165], v[192:195], v[98:101]
	v_mfma_f32_16x16x32_bf16 v[102:105], v[176:179], v[192:195], v[102:105]
	v_mfma_f32_16x16x32_bf16 v[82:85], v[162:165], v[206:209], v[82:85]
	v_mfma_f32_16x16x32_bf16 v[86:89], v[176:179], v[206:209], v[86:89]
	v_mfma_f32_16x16x32_bf16 v[66:69], v[162:165], v[214:217], v[66:69]
	v_mfma_f32_16x16x32_bf16 v[70:73], v[176:179], v[214:217], v[70:73]
	s_setprio 0
	s_barrier
; #define PG8_STAGE(bufoff, gbase, voff) do { _Pragma("unroll") for (int _i = 0; _i < 2; ++_i) \
;         __builtin_amdgcn_global_load_lds((const unsigned*)((const char*)(gbase) + (voff)[_i]), (PG8_LAS unsigned*)(lds + (bufoff) + ldsw + _i * 8192), 16, 0, 0); } while (0)
; #define PG8_LDA(dst, b, h) do { _Pragma("unroll") for (int m = 0; m < 4; ++m) _Pragma("unroll") for (int k = 0; k < 2; ++k) dst[m][k] = *(const PG8_LAS bf16x8*)(lds + PG8_SA(b, h) + aoff + m * 2048 + k * 1024); } while (0)
; #define PG8_MMA(ai, bj, At, Bt) do { __builtin_amdgcn_s_setprio(1); _Pragma("unroll") for (int m = 0; m < 4; ++m) _Pragma("unroll") for (int n = 0; n < 2; ++n) _Pragma("unroll") for (int k = 0; k < 2; ++k) \
;         acc[ai][bj][m][n] = __builtin_amdgcn_mfma_f32_16x16x32_bf16(Bt[n][k], At[m][k], acc[ai][bj][m][n], 0, 0, 0); __builtin_amdgcn_s_setprio(0); } while (0)
; #define PG8_WAIT_V(n) asm volatile("s_waitcnt vmcnt(" #n ")" ::: "memory")
; #define PG8_WAIT_L(n) asm volatile("s_waitcnt lgkmcnt(" #n ")" ::: "memory")
; #define PG8_BAR __builtin_amdgcn_s_barrier()
; #define PG8_SCHED __builtin_amdgcn_sched_barrier(0)
; template <class Epi, class Sched, bool ALIGN_EPI = false, bool SP2 = false>
; __device__ __forceinline__ void gemm_phase(PG8_LAS unsigned char* lds, const Gemm g, const Sched& S, const Epi& E) {
;     ...
;         for (int t = 0; t < nt; t += 2) {
;     ...
;             PG8_LDA(At, 1, 1); PG8_STAGE(PG8_SB(1, 0), b3, voffB); PG8_STAGE(PG8_SB(1, 1), b3 + hstep, voffB); PG8_STAGE(PG8_SA(1, 0), a3, voffA);
;             PG8_WAIT_V(8); PG8_WAIT_L(0); PG8_BAR; PG8_MMA(1, 0, At, B0); PG8_MMA(1, 1, At, B1); PG8_BAR; PG8_SCHED;
	s_add_i32 s38, s38, s75
	v_lshl_add_u64 v[218:219], v[218:219], 0, s[30:31]
	s_mov_b32 m0, s38
	ds_read_b128 v[180:183], v170 offset:49152
	ds_read_b128 v[184:187], v170 offset:50176
	ds_read_b128 v[188:191], v170 offset:51200
	ds_read_b128 v[192:195], v170 offset:52224
	ds_read_b128 v[202:205], v170 offset:53248
	ds_read_b128 v[206:209], v170 offset:54272
	ds_read_b128 v[210:213], v170 offset:55296
	ds_read_b128 v[214:217], v170 offset:56320
	global_load_lds_dwordx4 v[218:219], off
	s_add_i32 m0, s38, 0x2000
	s_add_u32 s46, s46, 0x40080
	v_lshl_add_u64 v[218:219], v[220:221], 0, s[30:31]
	s_addc_u32 s47, s47, 0
	s_add_i32 s38, s39, s75
	global_load_lds_dwordx4 v[218:219], off
	v_lshl_add_u64 v[218:219], s[46:47], 0, v[134:135]
	s_mov_b32 m0, s38
	s_nop 0
	global_load_lds_dwordx4 v[218:219], off
	v_lshl_add_u64 v[218:219], s[46:47], 0, v[130:131]
	s_add_i32 m0, s38, 0x2000
	s_nop 0
	global_load_lds_dwordx4 v[218:219], off
	v_lshl_add_u64 v[218:219], v[222:223], 0, s[30:31]
	s_mov_b32 m0, s80
	s_nop 0
	global_load_lds_dwordx4 v[218:219], off
	v_lshl_add_u64 v[218:219], v[224:225], 0, s[30:31]
	s_mov_b32 m0, s81
	s_nop 0
	global_load_lds_dwordx4 v[218:219], off
	s_waitcnt vmcnt(8)
	s_waitcnt lgkmcnt(0)
	s_barrier
	s_setprio 1
	s_waitcnt lgkmcnt(0)
	v_mfma_f32_16x16x32_bf16 v[58:61], v[142:145], v[180:183], v[58:61]
	v_mfma_f32_16x16x32_bf16 v[62:65], v[150:153], v[180:183], v[62:65]
	v_mfma_f32_16x16x32_bf16 v[42:45], v[142:145], v[188:191], v[42:45]
	v_mfma_f32_16x16x32_bf16 v[46:49], v[150:153], v[188:191], v[46:49]
	v_mfma_f32_16x16x32_bf16 v[26:29], v[142:145], v[202:205], v[26:29]
	v_mfma_f32_16x16x32_bf16 v[30:33], v[150:153], v[202:205], v[30:33]
	v_mfma_f32_16x16x32_bf16 v[10:13], v[142:145], v[210:213], v[10:13]
	v_mfma_f32_16x16x32_bf16 v[14:17], v[150:153], v[210:213], v[14:17]
	v_mfma_f32_16x16x32_bf16 v[58:61], v[146:149], v[184:187], v[58:61]
	v_mfma_f32_16x16x32_bf16 v[62:65], v[154:157], v[184:187], v[62:65]
	v_mfma_f32_16x16x32_bf16 v[42:45], v[146:149], v[192:195], v[42:45]
	v_mfma_f32_16x16x32_bf16 v[46:49], v[154:157], v[192:195], v[46:49]
	v_mfma_f32_16x16x32_bf16 v[26:29], v[146:149], v[206:209], v[26:29]
	v_mfma_f32_16x16x32_bf16 v[30:33], v[154:157], v[206:209], v[30:33]
	v_mfma_f32_16x16x32_bf16 v[10:13], v[146:149], v[214:217], v[10:13]
	v_mfma_f32_16x16x32_bf16 v[14:17], v[154:157], v[214:217], v[14:17]
	v_mfma_f32_16x16x32_bf16 v[50:53], v[158:161], v[180:183], v[50:53]
	v_mfma_f32_16x16x32_bf16 v[54:57], v[172:175], v[180:183], v[54:57]
	v_mfma_f32_16x16x32_bf16 v[34:37], v[158:161], v[188:191], v[34:37]
	v_mfma_f32_16x16x32_bf16 v[38:41], v[172:175], v[188:191], v[38:41]
	v_mfma_f32_16x16x32_bf16 v[18:21], v[158:161], v[202:205], v[18:21]
	v_mfma_f32_16x16x32_bf16 v[22:25], v[172:175], v[202:205], v[22:25]
	v_mfma_f32_16x16x32_bf16 v[2:5], v[158:161], v[210:213], v[2:5]
	v_mfma_f32_16x16x32_bf16 v[6:9], v[172:175], v[210:213], v[6:9]
	v_mfma_f32_16x16x32_bf16 v[50:53], v[162:165], v[184:187], v[50:53]
	v_mfma_f32_16x16x32_bf16 v[54:57], v[176:179], v[184:187], v[54:57]
	v_mfma_f32_16x16x32_bf16 v[34:37], v[162:165], v[192:195], v[34:37]
	v_mfma_f32_16x16x32_bf16 v[38:41], v[176:179], v[192:195], v[38:41]
	v_mfma_f32_16x16x32_bf16 v[18:21], v[162:165], v[206:209], v[18:21]
	v_mfma_f32_16x16x32_bf16 v[22:25], v[176:179], v[206:209], v[22:25]
	v_mfma_f32_16x16x32_bf16 v[2:5], v[162:165], v[214:217], v[2:5]
	v_mfma_f32_16x16x32_bf16 v[6:9], v[176:179], v[214:217], v[6:9]
	s_setprio 0
	s_barrier
	s_add_i32 s84, s84, 2
	s_add_u32 s48, s48, 0x100
	s_addc_u32 s49, s49, 0
	s_add_u32 s53, s53, 0x100
	s_addc_u32 s69, s69, 0
	s_cmp_gt_u32 s84, 13
	s_cbranch_scc0 .LBB0_408
	s_and_b64 vcc, exec, s[64:65]
	s_cbranch_vccz .LBB0_411
	s_barrier
